# v25 with chained MFMA pairs grouped by A fragment instead of by B fragment
# speedup vs baseline: 1.0063x; 1.0017x over previous
.LBB0_422:
	ds_read_b128 v[146:149], v154
	ds_read_b128 v[158:161], v154 offset:1024
	ds_read_b128 v[162:165], v154 offset:2048
	ds_read_b128 v[166:169], v154 offset:3072
	ds_read_b128 v[170:173], v155
	ds_read_b128 v[178:181], v155 offset:1024
	ds_read_b128 v[182:185], v155 offset:2048
	ds_read_b128 v[186:189], v155 offset:3072
	s_add_u32 s30, s28, 0xfc000
	s_addc_u32 s31, s29, 0
	s_cmp_eq_u32 s53, 60
	s_cselect_b32 s36, s21, s30
	s_cselect_b32 s37, s9, s31
	s_cselect_b32 s34, s50, s51
	s_cselect_b32 s35, s19, s52
	s_add_u32 s30, s36, 0x100000
	s_addc_u32 s31, s37, 0
	s_add_i32 m0, s1, 0xc000
	ds_read_b128 v[190:193], v156
	ds_read_b128 v[194:197], v156 offset:1024
	ds_read_b128 v[198:201], v156 offset:2048
	ds_read_b128 v[202:205], v156 offset:3072
	ds_read_b128 v[206:209], v156 offset:4096
	ds_read_b128 v[210:213], v156 offset:5120
	ds_read_b128 v[214:217], v156 offset:6144
	ds_read_b128 v[218:221], v156 offset:7168
	global_load_lds_dwordx4 v138, s[28:29]
	s_add_i32 m0, s1, 0xe000
	s_nop 0
	global_load_lds_dwordx4 v140, s[28:29]
	s_waitcnt vmcnt(8)
	s_waitcnt lgkmcnt(0)
	s_setprio 1
	s_barrier
	v_mfma_f32_16x16x32_bf16 v[126:129], v[146:149], v[190:193], v[126:129]
	v_mfma_f32_16x16x32_bf16 v[126:129], v[158:161], v[194:197], v[126:129]
	v_mfma_f32_16x16x32_bf16 v[110:113], v[146:149], v[198:201], v[110:113]
	v_mfma_f32_16x16x32_bf16 v[110:113], v[158:161], v[202:205], v[110:113]
	v_mfma_f32_16x16x32_bf16 v[94:97], v[146:149], v[206:209], v[94:97]
	v_mfma_f32_16x16x32_bf16 v[94:97], v[158:161], v[210:213], v[94:97]
	v_mfma_f32_16x16x32_bf16 v[78:81], v[146:149], v[214:217], v[78:81]
	v_mfma_f32_16x16x32_bf16 v[78:81], v[158:161], v[218:221], v[78:81]
	v_mfma_f32_16x16x32_bf16 v[122:125], v[162:165], v[190:193], v[122:125]
	v_mfma_f32_16x16x32_bf16 v[122:125], v[166:169], v[194:197], v[122:125]
	v_mfma_f32_16x16x32_bf16 v[106:109], v[162:165], v[198:201], v[106:109]
	v_mfma_f32_16x16x32_bf16 v[106:109], v[166:169], v[202:205], v[106:109]
	v_mfma_f32_16x16x32_bf16 v[90:93], v[162:165], v[206:209], v[90:93]
	v_mfma_f32_16x16x32_bf16 v[90:93], v[166:169], v[210:213], v[90:93]
	v_mfma_f32_16x16x32_bf16 v[74:77], v[162:165], v[214:217], v[74:77]
	v_mfma_f32_16x16x32_bf16 v[74:77], v[166:169], v[218:221], v[74:77]
	s_setprio 0
	s_setprio 1
	v_mfma_f32_16x16x32_bf16 v[118:121], v[170:173], v[190:193], v[118:121]
	v_mfma_f32_16x16x32_bf16 v[118:121], v[178:181], v[194:197], v[118:121]
	v_mfma_f32_16x16x32_bf16 v[102:105], v[170:173], v[198:201], v[102:105]
	v_mfma_f32_16x16x32_bf16 v[102:105], v[178:181], v[202:205], v[102:105]
	v_mfma_f32_16x16x32_bf16 v[86:89], v[170:173], v[206:209], v[86:89]
	v_mfma_f32_16x16x32_bf16 v[86:89], v[178:181], v[210:213], v[86:89]
	v_mfma_f32_16x16x32_bf16 v[70:73], v[170:173], v[214:217], v[70:73]
	v_mfma_f32_16x16x32_bf16 v[70:73], v[178:181], v[218:221], v[70:73]
	v_mfma_f32_16x16x32_bf16 v[114:117], v[182:185], v[190:193], v[114:117]
	v_mfma_f32_16x16x32_bf16 v[114:117], v[186:189], v[194:197], v[114:117]
	v_mfma_f32_16x16x32_bf16 v[98:101], v[182:185], v[198:201], v[98:101]
	v_mfma_f32_16x16x32_bf16 v[98:101], v[186:189], v[202:205], v[98:101]
	v_mfma_f32_16x16x32_bf16 v[82:85], v[182:185], v[206:209], v[82:85]
	v_mfma_f32_16x16x32_bf16 v[82:85], v[186:189], v[210:213], v[82:85]
	v_mfma_f32_16x16x32_bf16 v[66:69], v[182:185], v[214:217], v[66:69]
	v_mfma_f32_16x16x32_bf16 v[66:69], v[186:189], v[218:221], v[66:69]
	s_barrier
	s_setprio 0
	s_add_i32 s54, s48, s0
	s_mov_b32 m0, s54
	ds_read_b128 v[190:193], v156 offset:16384
	ds_read_b128 v[194:197], v156 offset:17408
	ds_read_b128 v[198:201], v156 offset:18432
	ds_read_b128 v[202:205], v156 offset:19456
	ds_read_b128 v[206:209], v156 offset:20480
	ds_read_b128 v[210:213], v156 offset:21504
	ds_read_b128 v[214:217], v156 offset:22528
	ds_read_b128 v[218:221], v156 offset:23552
	global_load_lds_dwordx4 v132, s[34:35]
	s_add_i32 m0, s54, 0x2000
	s_add_u32 s54, s34, 0x4000
	s_addc_u32 s55, s35, 0
	s_add_i32 s56, s49, s0
	global_load_lds_dwordx4 v136, s[34:35]
	s_mov_b32 m0, s56
	s_nop 0
	global_load_lds_dwordx4 v132, s[54:55]
	s_add_i32 m0, s56, 0x2000
	s_nop 0
	global_load_lds_dwordx4 v136, s[54:55]
	s_mov_b32 m0, s1
	s_nop 0
	global_load_lds_dwordx4 v130, s[36:37]
	s_mov_b32 m0, s27
	s_nop 0
	global_load_lds_dwordx4 v134, s[36:37]
	s_waitcnt vmcnt(8)
	s_waitcnt lgkmcnt(0)
	s_setprio 1
	s_barrier
	v_mfma_f32_16x16x32_bf16 v[62:65], v[146:149], v[190:193], v[62:65]
	v_mfma_f32_16x16x32_bf16 v[62:65], v[158:161], v[194:197], v[62:65]
	v_mfma_f32_16x16x32_bf16 v[46:49], v[146:149], v[198:201], v[46:49]
	v_mfma_f32_16x16x32_bf16 v[46:49], v[158:161], v[202:205], v[46:49]
	v_mfma_f32_16x16x32_bf16 v[30:33], v[146:149], v[206:209], v[30:33]
	v_mfma_f32_16x16x32_bf16 v[30:33], v[158:161], v[210:213], v[30:33]
	v_mfma_f32_16x16x32_bf16 v[14:17], v[146:149], v[214:217], v[14:17]
	v_mfma_f32_16x16x32_bf16 v[14:17], v[158:161], v[218:221], v[14:17]
	v_mfma_f32_16x16x32_bf16 v[58:61], v[162:165], v[190:193], v[58:61]
	v_mfma_f32_16x16x32_bf16 v[58:61], v[166:169], v[194:197], v[58:61]
	v_mfma_f32_16x16x32_bf16 v[42:45], v[162:165], v[198:201], v[42:45]
	v_mfma_f32_16x16x32_bf16 v[42:45], v[166:169], v[202:205], v[42:45]
	v_mfma_f32_16x16x32_bf16 v[26:29], v[162:165], v[206:209], v[26:29]
	v_mfma_f32_16x16x32_bf16 v[26:29], v[166:169], v[210:213], v[26:29]
	v_mfma_f32_16x16x32_bf16 v[10:13], v[162:165], v[214:217], v[10:13]
	v_mfma_f32_16x16x32_bf16 v[10:13], v[166:169], v[218:221], v[10:13]
	s_setprio 0
	s_setprio 1
	v_mfma_f32_16x16x32_bf16 v[54:57], v[170:173], v[190:193], v[54:57]
	v_mfma_f32_16x16x32_bf16 v[54:57], v[178:181], v[194:197], v[54:57]
	v_mfma_f32_16x16x32_bf16 v[38:41], v[170:173], v[198:201], v[38:41]
	v_mfma_f32_16x16x32_bf16 v[38:41], v[178:181], v[202:205], v[38:41]
	v_mfma_f32_16x16x32_bf16 v[22:25], v[170:173], v[206:209], v[22:25]
	v_mfma_f32_16x16x32_bf16 v[22:25], v[178:181], v[210:213], v[22:25]
	v_mfma_f32_16x16x32_bf16 v[6:9], v[170:173], v[214:217], v[6:9]
	v_mfma_f32_16x16x32_bf16 v[6:9], v[178:181], v[218:221], v[6:9]
	v_mfma_f32_16x16x32_bf16 v[50:53], v[182:185], v[190:193], v[50:53]
	v_mfma_f32_16x16x32_bf16 v[50:53], v[186:189], v[194:197], v[50:53]
	v_mfma_f32_16x16x32_bf16 v[34:37], v[182:185], v[198:201], v[34:37]
	v_mfma_f32_16x16x32_bf16 v[34:37], v[186:189], v[202:205], v[34:37]
	v_mfma_f32_16x16x32_bf16 v[18:21], v[182:185], v[206:209], v[18:21]
	v_mfma_f32_16x16x32_bf16 v[18:21], v[186:189], v[210:213], v[18:21]
	v_mfma_f32_16x16x32_bf16 v[2:5], v[182:185], v[214:217], v[2:5]
	v_mfma_f32_16x16x32_bf16 v[2:5], v[186:189], v[218:221], v[2:5]
	s_barrier
	s_setprio 0
	s_add_i32 s54, 0, 0x18000
	v_add_u32_e32 v150, s54, v153
	s_add_i32 s55, 0, 0x1c000
	ds_read_b128 v[146:149], v150
	ds_read_b128 v[158:161], v150 offset:1024
	ds_read_b128 v[162:165], v150 offset:2048
	ds_read_b128 v[166:169], v150 offset:3072
	v_add_u32_e32 v150, s55, v153
	ds_read_b128 v[170:173], v150
	ds_read_b128 v[178:181], v150 offset:1024
	ds_read_b128 v[182:185], v150 offset:2048
	ds_read_b128 v[186:189], v150 offset:3072
	s_add_u32 s36, s36, 0x4000
	s_addc_u32 s37, s37, 0
	s_mov_b32 m0, s33
	ds_read_b128 v[190:193], v156 offset:32768
	ds_read_b128 v[194:197], v156 offset:33792
	ds_read_b128 v[198:201], v156 offset:34816
	ds_read_b128 v[202:205], v156 offset:35840
	ds_read_b128 v[206:209], v156 offset:36864
	ds_read_b128 v[210:213], v156 offset:37888
	ds_read_b128 v[214:217], v156 offset:38912
	ds_read_b128 v[218:221], v156 offset:39936
	global_load_lds_dwordx4 v130, s[36:37]
	s_mov_b32 m0, s38
	s_nop 0
	global_load_lds_dwordx4 v134, s[36:37]
	s_waitcnt vmcnt(8)
	s_waitcnt lgkmcnt(0)
	s_setprio 1
	s_barrier
	v_mfma_f32_16x16x32_bf16 v[126:129], v[146:149], v[190:193], v[126:129]
	v_mfma_f32_16x16x32_bf16 v[126:129], v[158:161], v[194:197], v[126:129]
	v_mfma_f32_16x16x32_bf16 v[110:113], v[146:149], v[198:201], v[110:113]
	v_mfma_f32_16x16x32_bf16 v[110:113], v[158:161], v[202:205], v[110:113]
	v_mfma_f32_16x16x32_bf16 v[94:97], v[146:149], v[206:209], v[94:97]
	v_mfma_f32_16x16x32_bf16 v[94:97], v[158:161], v[210:213], v[94:97]
	v_mfma_f32_16x16x32_bf16 v[78:81], v[146:149], v[214:217], v[78:81]
	v_mfma_f32_16x16x32_bf16 v[78:81], v[158:161], v[218:221], v[78:81]
	v_mfma_f32_16x16x32_bf16 v[122:125], v[162:165], v[190:193], v[122:125]
	v_mfma_f32_16x16x32_bf16 v[122:125], v[166:169], v[194:197], v[122:125]
	v_mfma_f32_16x16x32_bf16 v[106:109], v[162:165], v[198:201], v[106:109]
	v_mfma_f32_16x16x32_bf16 v[106:109], v[166:169], v[202:205], v[106:109]
	v_mfma_f32_16x16x32_bf16 v[90:93], v[162:165], v[206:209], v[90:93]
	v_mfma_f32_16x16x32_bf16 v[90:93], v[166:169], v[210:213], v[90:93]
	v_mfma_f32_16x16x32_bf16 v[74:77], v[162:165], v[214:217], v[74:77]
	v_mfma_f32_16x16x32_bf16 v[74:77], v[166:169], v[218:221], v[74:77]
	s_setprio 0
	s_setprio 1
	v_mfma_f32_16x16x32_bf16 v[118:121], v[170:173], v[190:193], v[118:121]
	v_mfma_f32_16x16x32_bf16 v[118:121], v[178:181], v[194:197], v[118:121]
	v_mfma_f32_16x16x32_bf16 v[102:105], v[170:173], v[198:201], v[102:105]
	v_mfma_f32_16x16x32_bf16 v[102:105], v[178:181], v[202:205], v[102:105]
	v_mfma_f32_16x16x32_bf16 v[86:89], v[170:173], v[206:209], v[86:89]
	v_mfma_f32_16x16x32_bf16 v[86:89], v[178:181], v[210:213], v[86:89]
	v_mfma_f32_16x16x32_bf16 v[70:73], v[170:173], v[214:217], v[70:73]
	v_mfma_f32_16x16x32_bf16 v[70:73], v[178:181], v[218:221], v[70:73]
	v_mfma_f32_16x16x32_bf16 v[114:117], v[182:185], v[190:193], v[114:117]
	v_mfma_f32_16x16x32_bf16 v[114:117], v[186:189], v[194:197], v[114:117]
	v_mfma_f32_16x16x32_bf16 v[98:101], v[182:185], v[198:201], v[98:101]
	v_mfma_f32_16x16x32_bf16 v[98:101], v[186:189], v[202:205], v[98:101]
	v_mfma_f32_16x16x32_bf16 v[82:85], v[182:185], v[206:209], v[82:85]
	v_mfma_f32_16x16x32_bf16 v[82:85], v[186:189], v[210:213], v[82:85]
	v_mfma_f32_16x16x32_bf16 v[66:69], v[182:185], v[214:217], v[66:69]
	v_mfma_f32_16x16x32_bf16 v[66:69], v[186:189], v[218:221], v[66:69]
	s_barrier
	s_setprio 0
	s_add_u32 s36, s34, 0x380000
	s_addc_u32 s37, s35, 0
	s_add_i32 s54, s54, s0
	s_mov_b32 m0, s54
	ds_read_b128 v[190:193], v156 offset:49152
	ds_read_b128 v[194:197], v156 offset:50176
	ds_read_b128 v[198:201], v156 offset:51200
	ds_read_b128 v[202:205], v156 offset:52224
	ds_read_b128 v[206:209], v156 offset:53248
	ds_read_b128 v[210:213], v156 offset:54272
	ds_read_b128 v[214:217], v156 offset:55296
	ds_read_b128 v[218:221], v156 offset:56320
	global_load_lds_dwordx4 v132, s[36:37]
	s_add_i32 m0, s54, 0x2000
	s_add_u32 s34, s34, 0x384000
	s_addc_u32 s35, s35, 0
	global_load_lds_dwordx4 v136, s[36:37]
	s_add_i32 s36, s55, s0
	s_mov_b32 m0, s36
	s_nop 0
	global_load_lds_dwordx4 v132, s[34:35]
	s_add_i32 m0, s36, 0x2000
	s_nop 0
	global_load_lds_dwordx4 v136, s[34:35]
	s_mov_b32 m0, s44
	s_nop 0
	global_load_lds_dwordx4 v130, s[30:31]
	s_mov_b32 m0, s45
	s_nop 0
	global_load_lds_dwordx4 v134, s[30:31]
	s_waitcnt vmcnt(8)
	s_waitcnt lgkmcnt(0)
	s_setprio 1
	s_barrier
	v_mfma_f32_16x16x32_bf16 v[62:65], v[146:149], v[190:193], v[62:65]
	v_mfma_f32_16x16x32_bf16 v[62:65], v[158:161], v[194:197], v[62:65]
	v_mfma_f32_16x16x32_bf16 v[46:49], v[146:149], v[198:201], v[46:49]
	v_mfma_f32_16x16x32_bf16 v[46:49], v[158:161], v[202:205], v[46:49]
	v_mfma_f32_16x16x32_bf16 v[30:33], v[146:149], v[206:209], v[30:33]
	v_mfma_f32_16x16x32_bf16 v[30:33], v[158:161], v[210:213], v[30:33]
	v_mfma_f32_16x16x32_bf16 v[14:17], v[146:149], v[214:217], v[14:17]
	v_mfma_f32_16x16x32_bf16 v[14:17], v[158:161], v[218:221], v[14:17]
	v_mfma_f32_16x16x32_bf16 v[58:61], v[162:165], v[190:193], v[58:61]
	v_mfma_f32_16x16x32_bf16 v[58:61], v[166:169], v[194:197], v[58:61]
	v_mfma_f32_16x16x32_bf16 v[42:45], v[162:165], v[198:201], v[42:45]
	v_mfma_f32_16x16x32_bf16 v[42:45], v[166:169], v[202:205], v[42:45]
	v_mfma_f32_16x16x32_bf16 v[26:29], v[162:165], v[206:209], v[26:29]
	v_mfma_f32_16x16x32_bf16 v[26:29], v[166:169], v[210:213], v[26:29]
	v_mfma_f32_16x16x32_bf16 v[10:13], v[162:165], v[214:217], v[10:13]
	v_mfma_f32_16x16x32_bf16 v[10:13], v[166:169], v[218:221], v[10:13]
	s_setprio 0
	s_setprio 1
	v_mfma_f32_16x16x32_bf16 v[54:57], v[170:173], v[190:193], v[54:57]
	v_mfma_f32_16x16x32_bf16 v[54:57], v[178:181], v[194:197], v[54:57]
	v_mfma_f32_16x16x32_bf16 v[38:41], v[170:173], v[198:201], v[38:41]
	v_mfma_f32_16x16x32_bf16 v[38:41], v[178:181], v[202:205], v[38:41]
	v_mfma_f32_16x16x32_bf16 v[22:25], v[170:173], v[206:209], v[22:25]
	v_mfma_f32_16x16x32_bf16 v[22:25], v[178:181], v[210:213], v[22:25]
	v_mfma_f32_16x16x32_bf16 v[6:9], v[170:173], v[214:217], v[6:9]
	v_mfma_f32_16x16x32_bf16 v[6:9], v[178:181], v[218:221], v[6:9]
	v_mfma_f32_16x16x32_bf16 v[50:53], v[182:185], v[190:193], v[50:53]
	v_mfma_f32_16x16x32_bf16 v[50:53], v[186:189], v[194:197], v[50:53]
	v_mfma_f32_16x16x32_bf16 v[34:37], v[182:185], v[198:201], v[34:37]
	v_mfma_f32_16x16x32_bf16 v[34:37], v[186:189], v[202:205], v[34:37]
	v_mfma_f32_16x16x32_bf16 v[18:21], v[182:185], v[206:209], v[18:21]
	v_mfma_f32_16x16x32_bf16 v[18:21], v[186:189], v[210:213], v[18:21]
	v_mfma_f32_16x16x32_bf16 v[2:5], v[182:185], v[214:217], v[2:5]
	v_mfma_f32_16x16x32_bf16 v[2:5], v[186:189], v[218:221], v[2:5]
	s_barrier
	s_setprio 0
	s_add_i32 s53, s53, 2
	s_add_u32 s51, s51, 0x700000
	s_addc_u32 s52, s52, 0
	s_add_u32 s28, s28, 0x200000
	s_addc_u32 s29, s29, 0
	s_cmp_gt_u32 s53, 61
	s_cbranch_scc0 .LBB0_422
	s_and_b64 vcc, exec, s[16:17]
	s_cbranch_vccz .LBB0_425
	s_barrier

.LBB0_501:
	ds_read_b128 v[146:149], v152
	ds_read_b128 v[156:159], v152 offset:1024
	ds_read_b128 v[160:163], v152 offset:2048
	ds_read_b128 v[164:167], v152 offset:3072
	ds_read_b128 v[168:171], v153
	ds_read_b128 v[172:175], v153 offset:1024
	ds_read_b128 v[178:181], v153 offset:2048
	ds_read_b128 v[182:185], v153 offset:3072
	s_add_u32 s26, s10, 0xfc000
	s_addc_u32 s27, s11, 0
	s_cmpk_eq_i32 s47, 0xdc
	s_cselect_b32 s30, s21, s26
	s_cselect_b32 s31, s5, s27
	s_cselect_b32 s28, s44, s45
	s_cselect_b32 s29, s19, s46
	s_add_u32 s26, s30, 0x100000
	s_addc_u32 s27, s31, 0
	s_add_i32 m0, s1, 0xc000
	ds_read_b128 v[186:189], v154
	ds_read_b128 v[190:193], v154 offset:1024
	ds_read_b128 v[194:197], v154 offset:2048
	ds_read_b128 v[198:201], v154 offset:3072
	ds_read_b128 v[202:205], v154 offset:4096
	ds_read_b128 v[206:209], v154 offset:5120
	ds_read_b128 v[210:213], v154 offset:6144
	ds_read_b128 v[214:217], v154 offset:7168
	global_load_lds_dwordx4 v138, s[10:11]
	s_add_i32 m0, s1, 0xe000
	s_nop 0
	global_load_lds_dwordx4 v140, s[10:11]
	s_waitcnt vmcnt(8)
	s_waitcnt lgkmcnt(0)
	s_setprio 1
	s_barrier
	v_mfma_f32_16x16x32_bf16 v[126:129], v[146:149], v[186:189], v[126:129]
	v_mfma_f32_16x16x32_bf16 v[126:129], v[156:159], v[190:193], v[126:129]
	v_mfma_f32_16x16x32_bf16 v[110:113], v[146:149], v[194:197], v[110:113]
	v_mfma_f32_16x16x32_bf16 v[110:113], v[156:159], v[198:201], v[110:113]
	v_mfma_f32_16x16x32_bf16 v[94:97], v[146:149], v[202:205], v[94:97]
	v_mfma_f32_16x16x32_bf16 v[94:97], v[156:159], v[206:209], v[94:97]
	v_mfma_f32_16x16x32_bf16 v[78:81], v[146:149], v[210:213], v[78:81]
	v_mfma_f32_16x16x32_bf16 v[78:81], v[156:159], v[214:217], v[78:81]
	v_mfma_f32_16x16x32_bf16 v[122:125], v[160:163], v[186:189], v[122:125]
	v_mfma_f32_16x16x32_bf16 v[122:125], v[164:167], v[190:193], v[122:125]
	v_mfma_f32_16x16x32_bf16 v[106:109], v[160:163], v[194:197], v[106:109]
	v_mfma_f32_16x16x32_bf16 v[106:109], v[164:167], v[198:201], v[106:109]
	v_mfma_f32_16x16x32_bf16 v[90:93], v[160:163], v[202:205], v[90:93]
	v_mfma_f32_16x16x32_bf16 v[90:93], v[164:167], v[206:209], v[90:93]
	v_mfma_f32_16x16x32_bf16 v[74:77], v[160:163], v[210:213], v[74:77]
	v_mfma_f32_16x16x32_bf16 v[74:77], v[164:167], v[214:217], v[74:77]
	s_setprio 0
	s_setprio 1
	v_mfma_f32_16x16x32_bf16 v[118:121], v[168:171], v[186:189], v[118:121]
	v_mfma_f32_16x16x32_bf16 v[118:121], v[172:175], v[190:193], v[118:121]
	v_mfma_f32_16x16x32_bf16 v[102:105], v[168:171], v[194:197], v[102:105]
	v_mfma_f32_16x16x32_bf16 v[102:105], v[172:175], v[198:201], v[102:105]
	v_mfma_f32_16x16x32_bf16 v[86:89], v[168:171], v[202:205], v[86:89]
	v_mfma_f32_16x16x32_bf16 v[86:89], v[172:175], v[206:209], v[86:89]
	v_mfma_f32_16x16x32_bf16 v[70:73], v[168:171], v[210:213], v[70:73]
	v_mfma_f32_16x16x32_bf16 v[70:73], v[172:175], v[214:217], v[70:73]
	v_mfma_f32_16x16x32_bf16 v[114:117], v[178:181], v[186:189], v[114:117]
	v_mfma_f32_16x16x32_bf16 v[114:117], v[182:185], v[190:193], v[114:117]
	v_mfma_f32_16x16x32_bf16 v[98:101], v[178:181], v[194:197], v[98:101]
	v_mfma_f32_16x16x32_bf16 v[98:101], v[182:185], v[198:201], v[98:101]
	v_mfma_f32_16x16x32_bf16 v[82:85], v[178:181], v[202:205], v[82:85]
	v_mfma_f32_16x16x32_bf16 v[82:85], v[182:185], v[206:209], v[82:85]
	v_mfma_f32_16x16x32_bf16 v[66:69], v[178:181], v[210:213], v[66:69]
	v_mfma_f32_16x16x32_bf16 v[66:69], v[182:185], v[214:217], v[66:69]
	s_barrier
	s_setprio 0
	s_add_i32 s48, s41, s0
	s_mov_b32 m0, s48
	ds_read_b128 v[186:189], v154 offset:16384
	ds_read_b128 v[190:193], v154 offset:17408
	ds_read_b128 v[194:197], v154 offset:18432
	ds_read_b128 v[198:201], v154 offset:19456
	ds_read_b128 v[202:205], v154 offset:20480
	ds_read_b128 v[206:209], v154 offset:21504
	ds_read_b128 v[210:213], v154 offset:22528
	ds_read_b128 v[214:217], v154 offset:23552
	global_load_lds_dwordx4 v132, s[28:29]
	s_add_i32 m0, s48, 0x2000
	s_add_u32 s48, s28, 0x4000
	s_addc_u32 s49, s29, 0
	s_add_i32 s50, s42, s0
	global_load_lds_dwordx4 v136, s[28:29]
	s_mov_b32 m0, s50
	s_nop 0
	global_load_lds_dwordx4 v132, s[48:49]
	s_add_i32 m0, s50, 0x2000
	s_nop 0
	global_load_lds_dwordx4 v136, s[48:49]
	s_mov_b32 m0, s1
	s_nop 0
	global_load_lds_dwordx4 v130, s[30:31]
	s_mov_b32 m0, s33
	s_nop 0
	global_load_lds_dwordx4 v134, s[30:31]
	s_waitcnt vmcnt(8)
	s_waitcnt lgkmcnt(0)
	s_setprio 1
	s_barrier
	v_mfma_f32_16x16x32_bf16 v[62:65], v[146:149], v[186:189], v[62:65]
	v_mfma_f32_16x16x32_bf16 v[62:65], v[156:159], v[190:193], v[62:65]
	v_mfma_f32_16x16x32_bf16 v[46:49], v[146:149], v[194:197], v[46:49]
	v_mfma_f32_16x16x32_bf16 v[46:49], v[156:159], v[198:201], v[46:49]
	v_mfma_f32_16x16x32_bf16 v[30:33], v[146:149], v[202:205], v[30:33]
	v_mfma_f32_16x16x32_bf16 v[30:33], v[156:159], v[206:209], v[30:33]
	v_mfma_f32_16x16x32_bf16 v[14:17], v[146:149], v[210:213], v[14:17]
	v_mfma_f32_16x16x32_bf16 v[14:17], v[156:159], v[214:217], v[14:17]
	v_mfma_f32_16x16x32_bf16 v[58:61], v[160:163], v[186:189], v[58:61]
	v_mfma_f32_16x16x32_bf16 v[58:61], v[164:167], v[190:193], v[58:61]
	v_mfma_f32_16x16x32_bf16 v[42:45], v[160:163], v[194:197], v[42:45]
	v_mfma_f32_16x16x32_bf16 v[42:45], v[164:167], v[198:201], v[42:45]
	v_mfma_f32_16x16x32_bf16 v[26:29], v[160:163], v[202:205], v[26:29]
	v_mfma_f32_16x16x32_bf16 v[26:29], v[164:167], v[206:209], v[26:29]
	v_mfma_f32_16x16x32_bf16 v[10:13], v[160:163], v[210:213], v[10:13]
	v_mfma_f32_16x16x32_bf16 v[10:13], v[164:167], v[214:217], v[10:13]
	s_setprio 0
	s_setprio 1
	v_mfma_f32_16x16x32_bf16 v[54:57], v[168:171], v[186:189], v[54:57]
	v_mfma_f32_16x16x32_bf16 v[54:57], v[172:175], v[190:193], v[54:57]
	v_mfma_f32_16x16x32_bf16 v[38:41], v[168:171], v[194:197], v[38:41]
	v_mfma_f32_16x16x32_bf16 v[38:41], v[172:175], v[198:201], v[38:41]
	v_mfma_f32_16x16x32_bf16 v[22:25], v[168:171], v[202:205], v[22:25]
	v_mfma_f32_16x16x32_bf16 v[22:25], v[172:175], v[206:209], v[22:25]
	v_mfma_f32_16x16x32_bf16 v[6:9], v[168:171], v[210:213], v[6:9]
	v_mfma_f32_16x16x32_bf16 v[6:9], v[172:175], v[214:217], v[6:9]
	v_mfma_f32_16x16x32_bf16 v[50:53], v[178:181], v[186:189], v[50:53]
	v_mfma_f32_16x16x32_bf16 v[50:53], v[182:185], v[190:193], v[50:53]
	v_mfma_f32_16x16x32_bf16 v[34:37], v[178:181], v[194:197], v[34:37]
	v_mfma_f32_16x16x32_bf16 v[34:37], v[182:185], v[198:201], v[34:37]
	v_mfma_f32_16x16x32_bf16 v[18:21], v[178:181], v[202:205], v[18:21]
	v_mfma_f32_16x16x32_bf16 v[18:21], v[182:185], v[206:209], v[18:21]
	v_mfma_f32_16x16x32_bf16 v[2:5], v[178:181], v[210:213], v[2:5]
	v_mfma_f32_16x16x32_bf16 v[2:5], v[182:185], v[214:217], v[2:5]
	s_barrier
	s_setprio 0
	s_add_i32 s48, 0, 0x18000
	s_add_i32 s49, 0, 0x1c000
	v_add_u32_e32 v164, s48, v151
	v_add_u32_e32 v176, s49, v151
	ds_read_b128 v[146:149], v164
	ds_read_b128 v[156:159], v164 offset:1024
	ds_read_b128 v[160:163], v164 offset:2048
	ds_read_b128 v[164:167], v164 offset:3072
	ds_read_b128 v[168:171], v176
	ds_read_b128 v[172:175], v176 offset:1024
	ds_read_b128 v[178:181], v176 offset:2048
	ds_read_b128 v[182:185], v176 offset:3072
	s_add_u32 s30, s30, 0x4000
	s_addc_u32 s31, s31, 0
	s_mov_b32 m0, s34
	ds_read_b128 v[186:189], v154 offset:32768
	ds_read_b128 v[190:193], v154 offset:33792
	ds_read_b128 v[194:197], v154 offset:34816
	ds_read_b128 v[198:201], v154 offset:35840
	ds_read_b128 v[202:205], v154 offset:36864
	ds_read_b128 v[206:209], v154 offset:37888
	ds_read_b128 v[210:213], v154 offset:38912
	ds_read_b128 v[214:217], v154 offset:39936
	global_load_lds_dwordx4 v130, s[30:31]
	s_mov_b32 m0, s35
	s_nop 0
	global_load_lds_dwordx4 v134, s[30:31]
	s_waitcnt vmcnt(8)
	s_waitcnt lgkmcnt(0)
	s_setprio 1
	s_barrier
	v_mfma_f32_16x16x32_bf16 v[126:129], v[146:149], v[186:189], v[126:129]
	v_mfma_f32_16x16x32_bf16 v[126:129], v[156:159], v[190:193], v[126:129]
	v_mfma_f32_16x16x32_bf16 v[110:113], v[146:149], v[194:197], v[110:113]
	v_mfma_f32_16x16x32_bf16 v[110:113], v[156:159], v[198:201], v[110:113]
	v_mfma_f32_16x16x32_bf16 v[94:97], v[146:149], v[202:205], v[94:97]
	v_mfma_f32_16x16x32_bf16 v[94:97], v[156:159], v[206:209], v[94:97]
	v_mfma_f32_16x16x32_bf16 v[78:81], v[146:149], v[210:213], v[78:81]
	v_mfma_f32_16x16x32_bf16 v[78:81], v[156:159], v[214:217], v[78:81]
	v_mfma_f32_16x16x32_bf16 v[122:125], v[160:163], v[186:189], v[122:125]
	v_mfma_f32_16x16x32_bf16 v[122:125], v[164:167], v[190:193], v[122:125]
	v_mfma_f32_16x16x32_bf16 v[106:109], v[160:163], v[194:197], v[106:109]
	v_mfma_f32_16x16x32_bf16 v[106:109], v[164:167], v[198:201], v[106:109]
	v_mfma_f32_16x16x32_bf16 v[90:93], v[160:163], v[202:205], v[90:93]
	v_mfma_f32_16x16x32_bf16 v[90:93], v[164:167], v[206:209], v[90:93]
	v_mfma_f32_16x16x32_bf16 v[74:77], v[160:163], v[210:213], v[74:77]
	v_mfma_f32_16x16x32_bf16 v[74:77], v[164:167], v[214:217], v[74:77]
	s_setprio 0
	s_setprio 1
	v_mfma_f32_16x16x32_bf16 v[118:121], v[168:171], v[186:189], v[118:121]
	v_mfma_f32_16x16x32_bf16 v[118:121], v[172:175], v[190:193], v[118:121]
	v_mfma_f32_16x16x32_bf16 v[102:105], v[168:171], v[194:197], v[102:105]
	v_mfma_f32_16x16x32_bf16 v[102:105], v[172:175], v[198:201], v[102:105]
	v_mfma_f32_16x16x32_bf16 v[86:89], v[168:171], v[202:205], v[86:89]
	v_mfma_f32_16x16x32_bf16 v[86:89], v[172:175], v[206:209], v[86:89]
	v_mfma_f32_16x16x32_bf16 v[70:73], v[168:171], v[210:213], v[70:73]
	v_mfma_f32_16x16x32_bf16 v[70:73], v[172:175], v[214:217], v[70:73]
	v_mfma_f32_16x16x32_bf16 v[114:117], v[178:181], v[186:189], v[114:117]
	v_mfma_f32_16x16x32_bf16 v[114:117], v[182:185], v[190:193], v[114:117]
	v_mfma_f32_16x16x32_bf16 v[98:101], v[178:181], v[194:197], v[98:101]
	v_mfma_f32_16x16x32_bf16 v[98:101], v[182:185], v[198:201], v[98:101]
	v_mfma_f32_16x16x32_bf16 v[82:85], v[178:181], v[202:205], v[82:85]
	v_mfma_f32_16x16x32_bf16 v[82:85], v[182:185], v[206:209], v[82:85]
	v_mfma_f32_16x16x32_bf16 v[66:69], v[178:181], v[210:213], v[66:69]
	v_mfma_f32_16x16x32_bf16 v[66:69], v[182:185], v[214:217], v[66:69]
	s_barrier
	s_setprio 0
	s_add_u32 s30, s28, 0x80000
	s_addc_u32 s31, s29, 0
	s_add_i32 s48, s48, s0
	s_mov_b32 m0, s48
	ds_read_b128 v[186:189], v154 offset:49152
	ds_read_b128 v[190:193], v154 offset:50176
	ds_read_b128 v[194:197], v154 offset:51200
	ds_read_b128 v[198:201], v154 offset:52224
	ds_read_b128 v[202:205], v154 offset:53248
	ds_read_b128 v[206:209], v154 offset:54272
	ds_read_b128 v[210:213], v154 offset:55296
	ds_read_b128 v[214:217], v154 offset:56320
	global_load_lds_dwordx4 v132, s[30:31]
	s_add_i32 m0, s48, 0x2000
	s_add_u32 s28, s28, 0x84000
	s_addc_u32 s29, s29, 0
	global_load_lds_dwordx4 v136, s[30:31]
	s_add_i32 s30, s49, s0
	s_mov_b32 m0, s30
	s_nop 0
	global_load_lds_dwordx4 v132, s[28:29]
	s_add_i32 m0, s30, 0x2000
	s_nop 0
	global_load_lds_dwordx4 v136, s[28:29]
	s_mov_b32 m0, s39
	s_nop 0
	global_load_lds_dwordx4 v130, s[26:27]
	s_mov_b32 m0, s40
	s_nop 0
	global_load_lds_dwordx4 v134, s[26:27]
	s_waitcnt vmcnt(8)
	s_waitcnt lgkmcnt(0)
	s_setprio 1
	s_barrier
	v_mfma_f32_16x16x32_bf16 v[62:65], v[146:149], v[186:189], v[62:65]
	v_mfma_f32_16x16x32_bf16 v[62:65], v[156:159], v[190:193], v[62:65]
	v_mfma_f32_16x16x32_bf16 v[46:49], v[146:149], v[194:197], v[46:49]
	v_mfma_f32_16x16x32_bf16 v[46:49], v[156:159], v[198:201], v[46:49]
	v_mfma_f32_16x16x32_bf16 v[30:33], v[146:149], v[202:205], v[30:33]
	v_mfma_f32_16x16x32_bf16 v[30:33], v[156:159], v[206:209], v[30:33]
	v_mfma_f32_16x16x32_bf16 v[14:17], v[146:149], v[210:213], v[14:17]
	v_mfma_f32_16x16x32_bf16 v[14:17], v[156:159], v[214:217], v[14:17]
	v_mfma_f32_16x16x32_bf16 v[58:61], v[160:163], v[186:189], v[58:61]
	v_mfma_f32_16x16x32_bf16 v[58:61], v[164:167], v[190:193], v[58:61]
	v_mfma_f32_16x16x32_bf16 v[42:45], v[160:163], v[194:197], v[42:45]
	v_mfma_f32_16x16x32_bf16 v[42:45], v[164:167], v[198:201], v[42:45]
	v_mfma_f32_16x16x32_bf16 v[26:29], v[160:163], v[202:205], v[26:29]
	v_mfma_f32_16x16x32_bf16 v[26:29], v[164:167], v[206:209], v[26:29]
	v_mfma_f32_16x16x32_bf16 v[10:13], v[160:163], v[210:213], v[10:13]
	v_mfma_f32_16x16x32_bf16 v[10:13], v[164:167], v[214:217], v[10:13]
	s_setprio 0
	s_setprio 1
	v_mfma_f32_16x16x32_bf16 v[54:57], v[168:171], v[186:189], v[54:57]
	v_mfma_f32_16x16x32_bf16 v[54:57], v[172:175], v[190:193], v[54:57]
	v_mfma_f32_16x16x32_bf16 v[38:41], v[168:171], v[194:197], v[38:41]
	v_mfma_f32_16x16x32_bf16 v[38:41], v[172:175], v[198:201], v[38:41]
	v_mfma_f32_16x16x32_bf16 v[22:25], v[168:171], v[202:205], v[22:25]
	v_mfma_f32_16x16x32_bf16 v[22:25], v[172:175], v[206:209], v[22:25]
	v_mfma_f32_16x16x32_bf16 v[6:9], v[168:171], v[210:213], v[6:9]
	v_mfma_f32_16x16x32_bf16 v[6:9], v[172:175], v[214:217], v[6:9]
	v_mfma_f32_16x16x32_bf16 v[50:53], v[178:181], v[186:189], v[50:53]
	v_mfma_f32_16x16x32_bf16 v[50:53], v[182:185], v[190:193], v[50:53]
	v_mfma_f32_16x16x32_bf16 v[34:37], v[178:181], v[194:197], v[34:37]
	v_mfma_f32_16x16x32_bf16 v[34:37], v[182:185], v[198:201], v[34:37]
	v_mfma_f32_16x16x32_bf16 v[18:21], v[178:181], v[202:205], v[18:21]
	v_mfma_f32_16x16x32_bf16 v[18:21], v[182:185], v[206:209], v[18:21]
	v_mfma_f32_16x16x32_bf16 v[2:5], v[178:181], v[210:213], v[2:5]
	v_mfma_f32_16x16x32_bf16 v[2:5], v[182:185], v[214:217], v[2:5]
	s_barrier
	s_setprio 0
	s_add_i32 s47, s47, 2
	s_add_u32 s45, s45, 0x100000
	s_addc_u32 s46, s46, 0
	s_add_u32 s10, s10, 0x200000
	s_addc_u32 s11, s11, 0
	s_cmpk_gt_u32 s47, 0xdd
	s_cbranch_scc0 .LBB0_501
	s_and_b64 vcc, exec, s[16:17]
	s_cbranch_vccz .LBB0_504
	s_barrier

.LBB0_801:
	ds_read_b128 v[130:133], v179
	ds_read_b128 v[134:137], v179 offset:1024
	ds_read_b128 v[156:159], v179 offset:2048
	ds_read_b128 v[160:163], v179 offset:3072
	ds_read_b128 v[164:167], v180
	ds_read_b128 v[168:171], v180 offset:1024
	ds_read_b128 v[172:175], v180 offset:2048
	ds_read_b128 v[186:189], v180 offset:3072
	s_add_u32 s26, s12, 0xfc000
	s_addc_u32 s27, s13, 0
	s_cmp_eq_u32 s47, 60
	s_cselect_b32 s30, s5, s26
	s_cselect_b32 s31, s3, s27
	s_cselect_b32 s28, s21, s45
	s_cselect_b32 s29, s19, s46
	s_add_u32 s26, s30, 0x100000
	s_addc_u32 s27, s31, 0
	s_add_i32 m0, s1, 0xc000
	ds_read_b128 v[190:193], v181
	ds_read_b128 v[194:197], v181 offset:1024
	ds_read_b128 v[198:201], v181 offset:2048
	ds_read_b128 v[202:205], v181 offset:3072
	ds_read_b128 v[206:209], v181 offset:4096
	ds_read_b128 v[210:213], v181 offset:5120
	ds_read_b128 v[214:217], v181 offset:6144
	ds_read_b128 v[218:221], v181 offset:7168
	global_load_lds_dwordx4 v148, s[12:13]
	s_add_i32 m0, s1, 0xe000
	s_nop 0
	global_load_lds_dwordx4 v150, s[12:13]
	s_waitcnt vmcnt(8)
	s_waitcnt lgkmcnt(0)
	s_setprio 1
	s_barrier
	v_mfma_f32_16x16x32_bf16 v[126:129], v[130:133], v[190:193], v[126:129]
	v_mfma_f32_16x16x32_bf16 v[126:129], v[134:137], v[194:197], v[126:129]
	v_mfma_f32_16x16x32_bf16 v[110:113], v[130:133], v[198:201], v[110:113]
	v_mfma_f32_16x16x32_bf16 v[110:113], v[134:137], v[202:205], v[110:113]
	v_mfma_f32_16x16x32_bf16 v[94:97], v[130:133], v[206:209], v[94:97]
	v_mfma_f32_16x16x32_bf16 v[94:97], v[134:137], v[210:213], v[94:97]
	v_mfma_f32_16x16x32_bf16 v[78:81], v[130:133], v[214:217], v[78:81]
	v_mfma_f32_16x16x32_bf16 v[78:81], v[134:137], v[218:221], v[78:81]
	v_mfma_f32_16x16x32_bf16 v[122:125], v[156:159], v[190:193], v[122:125]
	v_mfma_f32_16x16x32_bf16 v[122:125], v[160:163], v[194:197], v[122:125]
	v_mfma_f32_16x16x32_bf16 v[106:109], v[156:159], v[198:201], v[106:109]
	v_mfma_f32_16x16x32_bf16 v[106:109], v[160:163], v[202:205], v[106:109]
	v_mfma_f32_16x16x32_bf16 v[90:93], v[156:159], v[206:209], v[90:93]
	v_mfma_f32_16x16x32_bf16 v[90:93], v[160:163], v[210:213], v[90:93]
	v_mfma_f32_16x16x32_bf16 v[74:77], v[156:159], v[214:217], v[74:77]
	v_mfma_f32_16x16x32_bf16 v[74:77], v[160:163], v[218:221], v[74:77]
	s_setprio 0
	s_setprio 1
	v_mfma_f32_16x16x32_bf16 v[118:121], v[164:167], v[190:193], v[118:121]
	v_mfma_f32_16x16x32_bf16 v[118:121], v[168:171], v[194:197], v[118:121]
	v_mfma_f32_16x16x32_bf16 v[102:105], v[164:167], v[198:201], v[102:105]
	v_mfma_f32_16x16x32_bf16 v[102:105], v[168:171], v[202:205], v[102:105]
	v_mfma_f32_16x16x32_bf16 v[86:89], v[164:167], v[206:209], v[86:89]
	v_mfma_f32_16x16x32_bf16 v[86:89], v[168:171], v[210:213], v[86:89]
	v_mfma_f32_16x16x32_bf16 v[70:73], v[164:167], v[214:217], v[70:73]
	v_mfma_f32_16x16x32_bf16 v[70:73], v[168:171], v[218:221], v[70:73]
	v_mfma_f32_16x16x32_bf16 v[114:117], v[172:175], v[190:193], v[114:117]
	v_mfma_f32_16x16x32_bf16 v[114:117], v[186:189], v[194:197], v[114:117]
	v_mfma_f32_16x16x32_bf16 v[98:101], v[172:175], v[198:201], v[98:101]
	v_mfma_f32_16x16x32_bf16 v[98:101], v[186:189], v[202:205], v[98:101]
	v_mfma_f32_16x16x32_bf16 v[82:85], v[172:175], v[206:209], v[82:85]
	v_mfma_f32_16x16x32_bf16 v[82:85], v[186:189], v[210:213], v[82:85]
	v_mfma_f32_16x16x32_bf16 v[66:69], v[172:175], v[214:217], v[66:69]
	v_mfma_f32_16x16x32_bf16 v[66:69], v[186:189], v[218:221], v[66:69]
	s_barrier
	s_setprio 0
	s_add_i32 s48, s42, s0
	s_mov_b32 m0, s48
	ds_read_b128 v[190:193], v181 offset:16384
	ds_read_b128 v[194:197], v181 offset:17408
	ds_read_b128 v[198:201], v181 offset:18432
	ds_read_b128 v[202:205], v181 offset:19456
	ds_read_b128 v[206:209], v181 offset:20480
	ds_read_b128 v[210:213], v181 offset:21504
	ds_read_b128 v[214:217], v181 offset:22528
	ds_read_b128 v[218:221], v181 offset:23552
	global_load_lds_dwordx4 v140, s[28:29]
	s_add_i32 m0, s48, 0x2000
	s_add_u32 s48, s28, 0x4000
	s_addc_u32 s49, s29, 0
	s_add_i32 s50, s43, s0
	global_load_lds_dwordx4 v144, s[28:29]
	s_mov_b32 m0, s50
	s_nop 0
	global_load_lds_dwordx4 v140, s[48:49]
	s_add_i32 m0, s50, 0x2000
	s_nop 0
	global_load_lds_dwordx4 v144, s[48:49]
	s_mov_b32 m0, s1
	s_nop 0
	global_load_lds_dwordx4 v138, s[30:31]
	s_mov_b32 m0, s33
	s_nop 0
	global_load_lds_dwordx4 v142, s[30:31]
	s_waitcnt vmcnt(8)
	s_waitcnt lgkmcnt(0)
	s_setprio 1
	s_barrier
	v_mfma_f32_16x16x32_bf16 v[62:65], v[130:133], v[190:193], v[62:65]
	v_mfma_f32_16x16x32_bf16 v[62:65], v[134:137], v[194:197], v[62:65]
	v_mfma_f32_16x16x32_bf16 v[46:49], v[130:133], v[198:201], v[46:49]
	v_mfma_f32_16x16x32_bf16 v[46:49], v[134:137], v[202:205], v[46:49]
	v_mfma_f32_16x16x32_bf16 v[30:33], v[130:133], v[206:209], v[30:33]
	v_mfma_f32_16x16x32_bf16 v[30:33], v[134:137], v[210:213], v[30:33]
	v_mfma_f32_16x16x32_bf16 v[14:17], v[130:133], v[214:217], v[14:17]
	v_mfma_f32_16x16x32_bf16 v[14:17], v[134:137], v[218:221], v[14:17]
	v_mfma_f32_16x16x32_bf16 v[58:61], v[156:159], v[190:193], v[58:61]
	v_mfma_f32_16x16x32_bf16 v[58:61], v[160:163], v[194:197], v[58:61]
	v_mfma_f32_16x16x32_bf16 v[42:45], v[156:159], v[198:201], v[42:45]
	v_mfma_f32_16x16x32_bf16 v[42:45], v[160:163], v[202:205], v[42:45]
	v_mfma_f32_16x16x32_bf16 v[26:29], v[156:159], v[206:209], v[26:29]
	v_mfma_f32_16x16x32_bf16 v[26:29], v[160:163], v[210:213], v[26:29]
	v_mfma_f32_16x16x32_bf16 v[10:13], v[156:159], v[214:217], v[10:13]
	v_mfma_f32_16x16x32_bf16 v[10:13], v[160:163], v[218:221], v[10:13]
	s_setprio 0
	s_setprio 1
	v_mfma_f32_16x16x32_bf16 v[54:57], v[164:167], v[190:193], v[54:57]
	v_mfma_f32_16x16x32_bf16 v[54:57], v[168:171], v[194:197], v[54:57]
	v_mfma_f32_16x16x32_bf16 v[38:41], v[164:167], v[198:201], v[38:41]
	v_mfma_f32_16x16x32_bf16 v[38:41], v[168:171], v[202:205], v[38:41]
	v_mfma_f32_16x16x32_bf16 v[22:25], v[164:167], v[206:209], v[22:25]
	v_mfma_f32_16x16x32_bf16 v[22:25], v[168:171], v[210:213], v[22:25]
	v_mfma_f32_16x16x32_bf16 v[6:9], v[164:167], v[214:217], v[6:9]
	v_mfma_f32_16x16x32_bf16 v[6:9], v[168:171], v[218:221], v[6:9]
	v_mfma_f32_16x16x32_bf16 v[50:53], v[172:175], v[190:193], v[50:53]
	v_mfma_f32_16x16x32_bf16 v[50:53], v[186:189], v[194:197], v[50:53]
	v_mfma_f32_16x16x32_bf16 v[34:37], v[172:175], v[198:201], v[34:37]
	v_mfma_f32_16x16x32_bf16 v[34:37], v[186:189], v[202:205], v[34:37]
	v_mfma_f32_16x16x32_bf16 v[18:21], v[172:175], v[206:209], v[18:21]
	v_mfma_f32_16x16x32_bf16 v[18:21], v[186:189], v[210:213], v[18:21]
	v_mfma_f32_16x16x32_bf16 v[2:5], v[172:175], v[214:217], v[2:5]
	v_mfma_f32_16x16x32_bf16 v[2:5], v[186:189], v[218:221], v[2:5]
	s_barrier
	s_setprio 0
	s_add_i32 s48, 0, 0x18000
	v_add_u32_e32 v146, s48, v178
	s_add_i32 s49, 0, 0x1c000
	ds_read_b128 v[130:133], v146
	ds_read_b128 v[134:137], v146 offset:1024
	ds_read_b128 v[156:159], v146 offset:2048
	ds_read_b128 v[160:163], v146 offset:3072
	v_add_u32_e32 v146, s49, v178
	ds_read_b128 v[164:167], v146
	ds_read_b128 v[168:171], v146 offset:1024
	ds_read_b128 v[172:175], v146 offset:2048
	ds_read_b128 v[186:189], v146 offset:3072
	s_add_u32 s30, s30, 0x4000
	s_addc_u32 s31, s31, 0
	s_mov_b32 m0, s34
	ds_read_b128 v[190:193], v181 offset:32768
	ds_read_b128 v[194:197], v181 offset:33792
	ds_read_b128 v[198:201], v181 offset:34816
	ds_read_b128 v[202:205], v181 offset:35840
	ds_read_b128 v[206:209], v181 offset:36864
	ds_read_b128 v[210:213], v181 offset:37888
	ds_read_b128 v[214:217], v181 offset:38912
	ds_read_b128 v[218:221], v181 offset:39936
	global_load_lds_dwordx4 v138, s[30:31]
	s_mov_b32 m0, s35
	s_nop 0
	global_load_lds_dwordx4 v142, s[30:31]
	s_waitcnt vmcnt(8)
	s_waitcnt lgkmcnt(0)
	s_setprio 1
	s_barrier
	v_mfma_f32_16x16x32_bf16 v[126:129], v[130:133], v[190:193], v[126:129]
	v_mfma_f32_16x16x32_bf16 v[126:129], v[134:137], v[194:197], v[126:129]
	v_mfma_f32_16x16x32_bf16 v[110:113], v[130:133], v[198:201], v[110:113]
	v_mfma_f32_16x16x32_bf16 v[110:113], v[134:137], v[202:205], v[110:113]
	v_mfma_f32_16x16x32_bf16 v[94:97], v[130:133], v[206:209], v[94:97]
	v_mfma_f32_16x16x32_bf16 v[94:97], v[134:137], v[210:213], v[94:97]
	v_mfma_f32_16x16x32_bf16 v[78:81], v[130:133], v[214:217], v[78:81]
	v_mfma_f32_16x16x32_bf16 v[78:81], v[134:137], v[218:221], v[78:81]
	v_mfma_f32_16x16x32_bf16 v[122:125], v[156:159], v[190:193], v[122:125]
	v_mfma_f32_16x16x32_bf16 v[122:125], v[160:163], v[194:197], v[122:125]
	v_mfma_f32_16x16x32_bf16 v[106:109], v[156:159], v[198:201], v[106:109]
	v_mfma_f32_16x16x32_bf16 v[106:109], v[160:163], v[202:205], v[106:109]
	v_mfma_f32_16x16x32_bf16 v[90:93], v[156:159], v[206:209], v[90:93]
	v_mfma_f32_16x16x32_bf16 v[90:93], v[160:163], v[210:213], v[90:93]
	v_mfma_f32_16x16x32_bf16 v[74:77], v[156:159], v[214:217], v[74:77]
	v_mfma_f32_16x16x32_bf16 v[74:77], v[160:163], v[218:221], v[74:77]
	s_setprio 0
	s_setprio 1
	v_mfma_f32_16x16x32_bf16 v[118:121], v[164:167], v[190:193], v[118:121]
	v_mfma_f32_16x16x32_bf16 v[118:121], v[168:171], v[194:197], v[118:121]
	v_mfma_f32_16x16x32_bf16 v[102:105], v[164:167], v[198:201], v[102:105]
	v_mfma_f32_16x16x32_bf16 v[102:105], v[168:171], v[202:205], v[102:105]
	v_mfma_f32_16x16x32_bf16 v[86:89], v[164:167], v[206:209], v[86:89]
	v_mfma_f32_16x16x32_bf16 v[86:89], v[168:171], v[210:213], v[86:89]
	v_mfma_f32_16x16x32_bf16 v[70:73], v[164:167], v[214:217], v[70:73]
	v_mfma_f32_16x16x32_bf16 v[70:73], v[168:171], v[218:221], v[70:73]
	v_mfma_f32_16x16x32_bf16 v[114:117], v[172:175], v[190:193], v[114:117]
	v_mfma_f32_16x16x32_bf16 v[114:117], v[186:189], v[194:197], v[114:117]
	v_mfma_f32_16x16x32_bf16 v[98:101], v[172:175], v[198:201], v[98:101]
	v_mfma_f32_16x16x32_bf16 v[98:101], v[186:189], v[202:205], v[98:101]
	v_mfma_f32_16x16x32_bf16 v[82:85], v[172:175], v[206:209], v[82:85]
	v_mfma_f32_16x16x32_bf16 v[82:85], v[186:189], v[210:213], v[82:85]
	v_mfma_f32_16x16x32_bf16 v[66:69], v[172:175], v[214:217], v[66:69]
	v_mfma_f32_16x16x32_bf16 v[66:69], v[186:189], v[218:221], v[66:69]
	s_barrier
	s_setprio 0
	s_add_u32 s30, s28, 0x180000
	s_addc_u32 s31, s29, 0
	s_add_i32 s48, s48, s0
	s_mov_b32 m0, s48
	ds_read_b128 v[190:193], v181 offset:49152
	ds_read_b128 v[194:197], v181 offset:50176
	ds_read_b128 v[198:201], v181 offset:51200
	ds_read_b128 v[202:205], v181 offset:52224
	ds_read_b128 v[206:209], v181 offset:53248
	ds_read_b128 v[210:213], v181 offset:54272
	ds_read_b128 v[214:217], v181 offset:55296
	ds_read_b128 v[218:221], v181 offset:56320
	global_load_lds_dwordx4 v140, s[30:31]
	s_add_i32 m0, s48, 0x2000
	s_add_u32 s28, s28, 0x184000
	s_addc_u32 s29, s29, 0
	global_load_lds_dwordx4 v144, s[30:31]
	s_add_i32 s30, s49, s0
	s_mov_b32 m0, s30
	s_nop 0
	global_load_lds_dwordx4 v140, s[28:29]
	s_add_i32 m0, s30, 0x2000
	s_nop 0
	global_load_lds_dwordx4 v144, s[28:29]
	s_mov_b32 m0, s38
	s_nop 0
	global_load_lds_dwordx4 v138, s[26:27]
	s_mov_b32 m0, s39
	s_nop 0
	global_load_lds_dwordx4 v142, s[26:27]
	s_waitcnt vmcnt(8)
	s_waitcnt lgkmcnt(0)
	s_setprio 1
	s_barrier
	v_mfma_f32_16x16x32_bf16 v[62:65], v[130:133], v[190:193], v[62:65]
	v_mfma_f32_16x16x32_bf16 v[62:65], v[134:137], v[194:197], v[62:65]
	v_mfma_f32_16x16x32_bf16 v[46:49], v[130:133], v[198:201], v[46:49]
	v_mfma_f32_16x16x32_bf16 v[46:49], v[134:137], v[202:205], v[46:49]
	v_mfma_f32_16x16x32_bf16 v[30:33], v[130:133], v[206:209], v[30:33]
	v_mfma_f32_16x16x32_bf16 v[30:33], v[134:137], v[210:213], v[30:33]
	v_mfma_f32_16x16x32_bf16 v[14:17], v[130:133], v[214:217], v[14:17]
	v_mfma_f32_16x16x32_bf16 v[14:17], v[134:137], v[218:221], v[14:17]
	v_mfma_f32_16x16x32_bf16 v[58:61], v[156:159], v[190:193], v[58:61]
	v_mfma_f32_16x16x32_bf16 v[58:61], v[160:163], v[194:197], v[58:61]
	v_mfma_f32_16x16x32_bf16 v[42:45], v[156:159], v[198:201], v[42:45]
	v_mfma_f32_16x16x32_bf16 v[42:45], v[160:163], v[202:205], v[42:45]
	v_mfma_f32_16x16x32_bf16 v[26:29], v[156:159], v[206:209], v[26:29]
	v_mfma_f32_16x16x32_bf16 v[26:29], v[160:163], v[210:213], v[26:29]
	v_mfma_f32_16x16x32_bf16 v[10:13], v[156:159], v[214:217], v[10:13]
	v_mfma_f32_16x16x32_bf16 v[10:13], v[160:163], v[218:221], v[10:13]
	s_setprio 0
	s_setprio 1
	v_mfma_f32_16x16x32_bf16 v[54:57], v[164:167], v[190:193], v[54:57]
	v_mfma_f32_16x16x32_bf16 v[54:57], v[168:171], v[194:197], v[54:57]
	v_mfma_f32_16x16x32_bf16 v[38:41], v[164:167], v[198:201], v[38:41]
	v_mfma_f32_16x16x32_bf16 v[38:41], v[168:171], v[202:205], v[38:41]
	v_mfma_f32_16x16x32_bf16 v[22:25], v[164:167], v[206:209], v[22:25]
	v_mfma_f32_16x16x32_bf16 v[22:25], v[168:171], v[210:213], v[22:25]
	v_mfma_f32_16x16x32_bf16 v[6:9], v[164:167], v[214:217], v[6:9]
	v_mfma_f32_16x16x32_bf16 v[6:9], v[168:171], v[218:221], v[6:9]
	v_mfma_f32_16x16x32_bf16 v[50:53], v[172:175], v[190:193], v[50:53]
	v_mfma_f32_16x16x32_bf16 v[50:53], v[186:189], v[194:197], v[50:53]
	v_mfma_f32_16x16x32_bf16 v[34:37], v[172:175], v[198:201], v[34:37]
	v_mfma_f32_16x16x32_bf16 v[34:37], v[186:189], v[202:205], v[34:37]
	v_mfma_f32_16x16x32_bf16 v[18:21], v[172:175], v[206:209], v[18:21]
	v_mfma_f32_16x16x32_bf16 v[18:21], v[186:189], v[210:213], v[18:21]
	v_mfma_f32_16x16x32_bf16 v[2:5], v[172:175], v[214:217], v[2:5]
	v_mfma_f32_16x16x32_bf16 v[2:5], v[186:189], v[218:221], v[2:5]
	s_barrier
	s_setprio 0
	s_add_i32 s47, s47, 2
	s_add_u32 s45, s45, 0x300000
	s_addc_u32 s46, s46, 0
	s_add_u32 s12, s12, 0x200000
	s_addc_u32 s13, s13, 0
	s_cmp_gt_u32 s47, 61
	s_cbranch_scc0 .LBB0_801
	s_and_b64 vcc, exec, s[8:9]
	s_cbranch_vccz .LBB0_804
	s_barrier

.LBB0_1217:
	ds_read_b128 v[146:149], v152
	ds_read_b128 v[156:159], v152 offset:1024
	ds_read_b128 v[160:163], v152 offset:2048
	ds_read_b128 v[164:167], v152 offset:3072
	ds_read_b128 v[168:171], v153
	ds_read_b128 v[172:175], v153 offset:1024
	ds_read_b128 v[176:179], v153 offset:2048
	ds_read_b128 v[180:183], v153 offset:3072
	s_add_u32 s22, s20, 0xfc000
	s_addc_u32 s23, s21, 0
	s_cmp_eq_u32 s43, 60
	s_cselect_b32 s26, s15, s22
	s_cselect_b32 s27, s5, s23
	s_cselect_b32 s24, s40, s41
	s_cselect_b32 s25, s13, s42
	s_add_u32 s22, s26, 0x100000
	s_addc_u32 s23, s27, 0
	s_add_i32 m0, s1, 0xc000
	ds_read_b128 v[184:187], v154
	ds_read_b128 v[188:191], v154 offset:1024
	ds_read_b128 v[192:195], v154 offset:2048
	ds_read_b128 v[196:199], v154 offset:3072
	ds_read_b128 v[206:209], v154 offset:4096
	ds_read_b128 v[212:215], v154 offset:5120
	ds_read_b128 v[220:223], v154 offset:6144
	ds_read_b128 v[224:227], v154 offset:7168
	global_load_lds_dwordx4 v138, s[20:21]
	s_add_i32 m0, s1, 0xe000
	s_nop 0
	global_load_lds_dwordx4 v140, s[20:21]
	s_waitcnt vmcnt(8)
	s_waitcnt lgkmcnt(0)
	s_setprio 1
	s_barrier
	v_mfma_f32_16x16x32_bf16 v[126:129], v[146:149], v[184:187], v[126:129]
	v_mfma_f32_16x16x32_bf16 v[126:129], v[156:159], v[188:191], v[126:129]
	v_mfma_f32_16x16x32_bf16 v[110:113], v[146:149], v[192:195], v[110:113]
	v_mfma_f32_16x16x32_bf16 v[110:113], v[156:159], v[196:199], v[110:113]
	v_mfma_f32_16x16x32_bf16 v[94:97], v[146:149], v[206:209], v[94:97]
	v_mfma_f32_16x16x32_bf16 v[94:97], v[156:159], v[212:215], v[94:97]
	v_mfma_f32_16x16x32_bf16 v[78:81], v[146:149], v[220:223], v[78:81]
	v_mfma_f32_16x16x32_bf16 v[78:81], v[156:159], v[224:227], v[78:81]
	v_mfma_f32_16x16x32_bf16 v[122:125], v[160:163], v[184:187], v[122:125]
	v_mfma_f32_16x16x32_bf16 v[122:125], v[164:167], v[188:191], v[122:125]
	v_mfma_f32_16x16x32_bf16 v[106:109], v[160:163], v[192:195], v[106:109]
	v_mfma_f32_16x16x32_bf16 v[106:109], v[164:167], v[196:199], v[106:109]
	v_mfma_f32_16x16x32_bf16 v[90:93], v[160:163], v[206:209], v[90:93]
	v_mfma_f32_16x16x32_bf16 v[90:93], v[164:167], v[212:215], v[90:93]
	v_mfma_f32_16x16x32_bf16 v[74:77], v[160:163], v[220:223], v[74:77]
	v_mfma_f32_16x16x32_bf16 v[74:77], v[164:167], v[224:227], v[74:77]
	s_setprio 0
	s_setprio 1
	v_mfma_f32_16x16x32_bf16 v[118:121], v[168:171], v[184:187], v[118:121]
	v_mfma_f32_16x16x32_bf16 v[118:121], v[172:175], v[188:191], v[118:121]
	v_mfma_f32_16x16x32_bf16 v[102:105], v[168:171], v[192:195], v[102:105]
	v_mfma_f32_16x16x32_bf16 v[102:105], v[172:175], v[196:199], v[102:105]
	v_mfma_f32_16x16x32_bf16 v[86:89], v[168:171], v[206:209], v[86:89]
	v_mfma_f32_16x16x32_bf16 v[86:89], v[172:175], v[212:215], v[86:89]
	v_mfma_f32_16x16x32_bf16 v[70:73], v[168:171], v[220:223], v[70:73]
	v_mfma_f32_16x16x32_bf16 v[70:73], v[172:175], v[224:227], v[70:73]
	v_mfma_f32_16x16x32_bf16 v[114:117], v[176:179], v[184:187], v[114:117]
	v_mfma_f32_16x16x32_bf16 v[114:117], v[180:183], v[188:191], v[114:117]
	v_mfma_f32_16x16x32_bf16 v[98:101], v[176:179], v[192:195], v[98:101]
	v_mfma_f32_16x16x32_bf16 v[98:101], v[180:183], v[196:199], v[98:101]
	v_mfma_f32_16x16x32_bf16 v[82:85], v[176:179], v[206:209], v[82:85]
	v_mfma_f32_16x16x32_bf16 v[82:85], v[180:183], v[212:215], v[82:85]
	v_mfma_f32_16x16x32_bf16 v[66:69], v[176:179], v[220:223], v[66:69]
	v_mfma_f32_16x16x32_bf16 v[66:69], v[180:183], v[224:227], v[66:69]
	s_barrier
	s_setprio 0
	s_add_i32 s44, s37, s0
	s_mov_b32 m0, s44
	ds_read_b128 v[184:187], v154 offset:16384
	ds_read_b128 v[188:191], v154 offset:17408
	ds_read_b128 v[192:195], v154 offset:18432
	ds_read_b128 v[196:199], v154 offset:19456
	ds_read_b128 v[206:209], v154 offset:20480
	ds_read_b128 v[212:215], v154 offset:21504
	ds_read_b128 v[220:223], v154 offset:22528
	ds_read_b128 v[224:227], v154 offset:23552
	global_load_lds_dwordx4 v132, s[24:25]
	s_add_i32 m0, s44, 0x2000
	s_add_u32 s44, s24, 0x4000
	s_addc_u32 s45, s25, 0
	s_add_i32 s46, s38, s0
	global_load_lds_dwordx4 v136, s[24:25]
	s_mov_b32 m0, s46
	s_nop 0
	global_load_lds_dwordx4 v132, s[44:45]
	s_add_i32 m0, s46, 0x2000
	s_nop 0
	global_load_lds_dwordx4 v136, s[44:45]
	s_mov_b32 m0, s1
	s_nop 0
	global_load_lds_dwordx4 v130, s[26:27]
	s_mov_b32 m0, s28
	s_nop 0
	global_load_lds_dwordx4 v134, s[26:27]
	s_waitcnt vmcnt(8)
	s_waitcnt lgkmcnt(0)
	s_setprio 1
	s_barrier
	v_mfma_f32_16x16x32_bf16 v[62:65], v[146:149], v[184:187], v[62:65]
	v_mfma_f32_16x16x32_bf16 v[62:65], v[156:159], v[188:191], v[62:65]
	v_mfma_f32_16x16x32_bf16 v[46:49], v[146:149], v[192:195], v[46:49]
	v_mfma_f32_16x16x32_bf16 v[46:49], v[156:159], v[196:199], v[46:49]
	v_mfma_f32_16x16x32_bf16 v[30:33], v[146:149], v[206:209], v[30:33]
	v_mfma_f32_16x16x32_bf16 v[30:33], v[156:159], v[212:215], v[30:33]
	v_mfma_f32_16x16x32_bf16 v[14:17], v[146:149], v[220:223], v[14:17]
	v_mfma_f32_16x16x32_bf16 v[14:17], v[156:159], v[224:227], v[14:17]
	v_mfma_f32_16x16x32_bf16 v[58:61], v[160:163], v[184:187], v[58:61]
	v_mfma_f32_16x16x32_bf16 v[58:61], v[164:167], v[188:191], v[58:61]
	v_mfma_f32_16x16x32_bf16 v[42:45], v[160:163], v[192:195], v[42:45]
	v_mfma_f32_16x16x32_bf16 v[42:45], v[164:167], v[196:199], v[42:45]
	v_mfma_f32_16x16x32_bf16 v[26:29], v[160:163], v[206:209], v[26:29]
	v_mfma_f32_16x16x32_bf16 v[26:29], v[164:167], v[212:215], v[26:29]
	v_mfma_f32_16x16x32_bf16 v[10:13], v[160:163], v[220:223], v[10:13]
	v_mfma_f32_16x16x32_bf16 v[10:13], v[164:167], v[224:227], v[10:13]
	s_setprio 0
	s_setprio 1
	v_mfma_f32_16x16x32_bf16 v[54:57], v[168:171], v[184:187], v[54:57]
	v_mfma_f32_16x16x32_bf16 v[54:57], v[172:175], v[188:191], v[54:57]
	v_mfma_f32_16x16x32_bf16 v[38:41], v[168:171], v[192:195], v[38:41]
	v_mfma_f32_16x16x32_bf16 v[38:41], v[172:175], v[196:199], v[38:41]
	v_mfma_f32_16x16x32_bf16 v[22:25], v[168:171], v[206:209], v[22:25]
	v_mfma_f32_16x16x32_bf16 v[22:25], v[172:175], v[212:215], v[22:25]
	v_mfma_f32_16x16x32_bf16 v[6:9], v[168:171], v[220:223], v[6:9]
	v_mfma_f32_16x16x32_bf16 v[6:9], v[172:175], v[224:227], v[6:9]
	v_mfma_f32_16x16x32_bf16 v[50:53], v[176:179], v[184:187], v[50:53]
	v_mfma_f32_16x16x32_bf16 v[50:53], v[180:183], v[188:191], v[50:53]
	v_mfma_f32_16x16x32_bf16 v[34:37], v[176:179], v[192:195], v[34:37]
	v_mfma_f32_16x16x32_bf16 v[34:37], v[180:183], v[196:199], v[34:37]
	v_mfma_f32_16x16x32_bf16 v[18:21], v[176:179], v[206:209], v[18:21]
	v_mfma_f32_16x16x32_bf16 v[18:21], v[180:183], v[212:215], v[18:21]
	v_mfma_f32_16x16x32_bf16 v[2:5], v[176:179], v[220:223], v[2:5]
	v_mfma_f32_16x16x32_bf16 v[2:5], v[180:183], v[224:227], v[2:5]
	s_barrier
	s_setprio 0
	s_add_i32 s44, 0, 0x18000
	v_add_u32_e32 v155, s44, v151
	s_add_i32 s45, 0, 0x1c000
	ds_read_b128 v[146:149], v155
	ds_read_b128 v[156:159], v155 offset:1024
	ds_read_b128 v[160:163], v155 offset:2048
	ds_read_b128 v[164:167], v155 offset:3072
	v_add_u32_e32 v155, s45, v151
	ds_read_b128 v[168:171], v155
	ds_read_b128 v[172:175], v155 offset:1024
	ds_read_b128 v[176:179], v155 offset:2048
	ds_read_b128 v[180:183], v155 offset:3072
	s_add_u32 s26, s26, 0x4000
	s_addc_u32 s27, s27, 0
	s_mov_b32 m0, s29
	ds_read_b128 v[184:187], v154 offset:32768
	ds_read_b128 v[188:191], v154 offset:33792
	ds_read_b128 v[192:195], v154 offset:34816
	ds_read_b128 v[196:199], v154 offset:35840
	ds_read_b128 v[206:209], v154 offset:36864
	ds_read_b128 v[212:215], v154 offset:37888
	ds_read_b128 v[220:223], v154 offset:38912
	ds_read_b128 v[224:227], v154 offset:39936
	global_load_lds_dwordx4 v130, s[26:27]
	s_mov_b32 m0, s30
	s_nop 0
	global_load_lds_dwordx4 v134, s[26:27]
	s_waitcnt vmcnt(8)
	s_waitcnt lgkmcnt(0)
	s_setprio 1
	s_barrier
	v_mfma_f32_16x16x32_bf16 v[126:129], v[146:149], v[184:187], v[126:129]
	v_mfma_f32_16x16x32_bf16 v[126:129], v[156:159], v[188:191], v[126:129]
	v_mfma_f32_16x16x32_bf16 v[110:113], v[146:149], v[192:195], v[110:113]
	v_mfma_f32_16x16x32_bf16 v[110:113], v[156:159], v[196:199], v[110:113]
	v_mfma_f32_16x16x32_bf16 v[94:97], v[146:149], v[206:209], v[94:97]
	v_mfma_f32_16x16x32_bf16 v[94:97], v[156:159], v[212:215], v[94:97]
	v_mfma_f32_16x16x32_bf16 v[78:81], v[146:149], v[220:223], v[78:81]
	v_mfma_f32_16x16x32_bf16 v[78:81], v[156:159], v[224:227], v[78:81]
	v_mfma_f32_16x16x32_bf16 v[122:125], v[160:163], v[184:187], v[122:125]
	v_mfma_f32_16x16x32_bf16 v[122:125], v[164:167], v[188:191], v[122:125]
	v_mfma_f32_16x16x32_bf16 v[106:109], v[160:163], v[192:195], v[106:109]
	v_mfma_f32_16x16x32_bf16 v[106:109], v[164:167], v[196:199], v[106:109]
	v_mfma_f32_16x16x32_bf16 v[90:93], v[160:163], v[206:209], v[90:93]
	v_mfma_f32_16x16x32_bf16 v[90:93], v[164:167], v[212:215], v[90:93]
	v_mfma_f32_16x16x32_bf16 v[74:77], v[160:163], v[220:223], v[74:77]
	v_mfma_f32_16x16x32_bf16 v[74:77], v[164:167], v[224:227], v[74:77]
	s_setprio 0
	s_setprio 1
	v_mfma_f32_16x16x32_bf16 v[118:121], v[168:171], v[184:187], v[118:121]
	v_mfma_f32_16x16x32_bf16 v[118:121], v[172:175], v[188:191], v[118:121]
	v_mfma_f32_16x16x32_bf16 v[102:105], v[168:171], v[192:195], v[102:105]
	v_mfma_f32_16x16x32_bf16 v[102:105], v[172:175], v[196:199], v[102:105]
	v_mfma_f32_16x16x32_bf16 v[86:89], v[168:171], v[206:209], v[86:89]
	v_mfma_f32_16x16x32_bf16 v[86:89], v[172:175], v[212:215], v[86:89]
	v_mfma_f32_16x16x32_bf16 v[70:73], v[168:171], v[220:223], v[70:73]
	v_mfma_f32_16x16x32_bf16 v[70:73], v[172:175], v[224:227], v[70:73]
	v_mfma_f32_16x16x32_bf16 v[114:117], v[176:179], v[184:187], v[114:117]
	v_mfma_f32_16x16x32_bf16 v[114:117], v[180:183], v[188:191], v[114:117]
	v_mfma_f32_16x16x32_bf16 v[98:101], v[176:179], v[192:195], v[98:101]
	v_mfma_f32_16x16x32_bf16 v[98:101], v[180:183], v[196:199], v[98:101]
	v_mfma_f32_16x16x32_bf16 v[82:85], v[176:179], v[206:209], v[82:85]
	v_mfma_f32_16x16x32_bf16 v[82:85], v[180:183], v[212:215], v[82:85]
	v_mfma_f32_16x16x32_bf16 v[66:69], v[176:179], v[220:223], v[66:69]
	v_mfma_f32_16x16x32_bf16 v[66:69], v[180:183], v[224:227], v[66:69]
	s_barrier
	s_setprio 0
	s_add_u32 s26, s24, 0x80000
	s_addc_u32 s27, s25, 0
	s_add_i32 s44, s44, s0
	s_mov_b32 m0, s44
	ds_read_b128 v[184:187], v154 offset:49152
	ds_read_b128 v[188:191], v154 offset:50176
	ds_read_b128 v[192:195], v154 offset:51200
	ds_read_b128 v[196:199], v154 offset:52224
	ds_read_b128 v[206:209], v154 offset:53248
	ds_read_b128 v[212:215], v154 offset:54272
	ds_read_b128 v[220:223], v154 offset:55296
	ds_read_b128 v[224:227], v154 offset:56320
	global_load_lds_dwordx4 v132, s[26:27]
	s_add_i32 m0, s44, 0x2000
	s_add_u32 s24, s24, 0x84000
	s_addc_u32 s25, s25, 0
	global_load_lds_dwordx4 v136, s[26:27]
	s_add_i32 s26, s45, s0
	s_mov_b32 m0, s26
	s_nop 0
	global_load_lds_dwordx4 v132, s[24:25]
	s_add_i32 m0, s26, 0x2000
	s_nop 0
	global_load_lds_dwordx4 v136, s[24:25]
	s_mov_b32 m0, s35
	s_nop 0
	global_load_lds_dwordx4 v130, s[22:23]
	s_mov_b32 m0, s36
	s_nop 0
	global_load_lds_dwordx4 v134, s[22:23]
	s_waitcnt vmcnt(8)
	s_waitcnt lgkmcnt(0)
	s_setprio 1
	s_barrier
	v_mfma_f32_16x16x32_bf16 v[62:65], v[146:149], v[184:187], v[62:65]
	v_mfma_f32_16x16x32_bf16 v[62:65], v[156:159], v[188:191], v[62:65]
	v_mfma_f32_16x16x32_bf16 v[46:49], v[146:149], v[192:195], v[46:49]
	v_mfma_f32_16x16x32_bf16 v[46:49], v[156:159], v[196:199], v[46:49]
	v_mfma_f32_16x16x32_bf16 v[30:33], v[146:149], v[206:209], v[30:33]
	v_mfma_f32_16x16x32_bf16 v[30:33], v[156:159], v[212:215], v[30:33]
	v_mfma_f32_16x16x32_bf16 v[14:17], v[146:149], v[220:223], v[14:17]
	v_mfma_f32_16x16x32_bf16 v[14:17], v[156:159], v[224:227], v[14:17]
	v_mfma_f32_16x16x32_bf16 v[58:61], v[160:163], v[184:187], v[58:61]
	v_mfma_f32_16x16x32_bf16 v[58:61], v[164:167], v[188:191], v[58:61]
	v_mfma_f32_16x16x32_bf16 v[42:45], v[160:163], v[192:195], v[42:45]
	v_mfma_f32_16x16x32_bf16 v[42:45], v[164:167], v[196:199], v[42:45]
	v_mfma_f32_16x16x32_bf16 v[26:29], v[160:163], v[206:209], v[26:29]
	v_mfma_f32_16x16x32_bf16 v[26:29], v[164:167], v[212:215], v[26:29]
	v_mfma_f32_16x16x32_bf16 v[10:13], v[160:163], v[220:223], v[10:13]
	v_mfma_f32_16x16x32_bf16 v[10:13], v[164:167], v[224:227], v[10:13]
	s_setprio 0
	s_setprio 1
	v_mfma_f32_16x16x32_bf16 v[54:57], v[168:171], v[184:187], v[54:57]
	v_mfma_f32_16x16x32_bf16 v[54:57], v[172:175], v[188:191], v[54:57]
	v_mfma_f32_16x16x32_bf16 v[38:41], v[168:171], v[192:195], v[38:41]
	v_mfma_f32_16x16x32_bf16 v[38:41], v[172:175], v[196:199], v[38:41]
	v_mfma_f32_16x16x32_bf16 v[22:25], v[168:171], v[206:209], v[22:25]
	v_mfma_f32_16x16x32_bf16 v[22:25], v[172:175], v[212:215], v[22:25]
	v_mfma_f32_16x16x32_bf16 v[6:9], v[168:171], v[220:223], v[6:9]
	v_mfma_f32_16x16x32_bf16 v[6:9], v[172:175], v[224:227], v[6:9]
	v_mfma_f32_16x16x32_bf16 v[50:53], v[176:179], v[184:187], v[50:53]
	v_mfma_f32_16x16x32_bf16 v[50:53], v[180:183], v[188:191], v[50:53]
	v_mfma_f32_16x16x32_bf16 v[34:37], v[176:179], v[192:195], v[34:37]
	v_mfma_f32_16x16x32_bf16 v[34:37], v[180:183], v[196:199], v[34:37]
	v_mfma_f32_16x16x32_bf16 v[18:21], v[176:179], v[206:209], v[18:21]
	v_mfma_f32_16x16x32_bf16 v[18:21], v[180:183], v[212:215], v[18:21]
	v_mfma_f32_16x16x32_bf16 v[2:5], v[176:179], v[220:223], v[2:5]
	v_mfma_f32_16x16x32_bf16 v[2:5], v[180:183], v[224:227], v[2:5]
	s_barrier
	s_setprio 0
	s_add_i32 s43, s43, 2
	s_add_u32 s41, s41, 0x100000
	s_addc_u32 s42, s42, 0
	s_add_u32 s20, s20, 0x200000
	s_addc_u32 s21, s21, 0
	s_cmp_gt_u32 s43, 61
	s_cbranch_scc0 .LBB0_1217
	s_and_b64 vcc, exec, s[8:9]
	s_cbranch_vccz .LBB0_1220
	s_barrier

.LBB0_1670:
	ds_read_b128 v[148:151], v143
	ds_read_b128 v[152:155], v143 offset:1024
	ds_read_b128 v[156:159], v143 offset:2048
	ds_read_b128 v[160:163], v143 offset:3072
	ds_read_b128 v[164:167], v144
	ds_read_b128 v[168:171], v144 offset:1024
	ds_read_b128 v[172:175], v144 offset:2048
	ds_read_b128 v[176:179], v144 offset:3072
	s_add_u32 s10, s6, 0x4000
	s_addc_u32 s11, s7, 0
	s_cmp_eq_u32 s28, 60
	s_cselect_b32 s18, s14, s10
	s_cselect_b32 s19, s15, s11
	s_cselect_b32 s16, s4, s26
	s_cselect_b32 s17, s5, s27
	s_add_u32 s10, s18, 0x8000
	s_addc_u32 s11, s19, 0
	s_mov_b32 m0, s29
	ds_read_b128 v[180:183], v145
	ds_read_b128 v[184:187], v145 offset:1024
	ds_read_b128 v[188:191], v145 offset:2048
	ds_read_b128 v[192:195], v145 offset:3072
	ds_read_b128 v[196:199], v145 offset:4096
	ds_read_b128 v[206:209], v145 offset:5120
	ds_read_b128 v[212:215], v145 offset:6144
	ds_read_b128 v[220:223], v145 offset:7168
	global_load_lds_dwordx4 v138, s[6:7]
	s_mov_b32 m0, s30
	s_nop 0
	global_load_lds_dwordx4 v140, s[6:7]
	s_waitcnt vmcnt(8)
	s_waitcnt lgkmcnt(0)
	s_setprio 1
	s_barrier
	v_mfma_f32_16x16x32_bf16 v[126:129], v[148:151], v[180:183], v[126:129]
	v_mfma_f32_16x16x32_bf16 v[126:129], v[152:155], v[184:187], v[126:129]
	v_mfma_f32_16x16x32_bf16 v[118:121], v[148:151], v[188:191], v[118:121]
	v_mfma_f32_16x16x32_bf16 v[118:121], v[152:155], v[192:195], v[118:121]
	v_mfma_f32_16x16x32_bf16 v[102:105], v[148:151], v[196:199], v[102:105]
	v_mfma_f32_16x16x32_bf16 v[102:105], v[152:155], v[206:209], v[102:105]
	v_mfma_f32_16x16x32_bf16 v[86:89], v[148:151], v[212:215], v[86:89]
	v_mfma_f32_16x16x32_bf16 v[86:89], v[152:155], v[220:223], v[86:89]
	v_mfma_f32_16x16x32_bf16 v[122:125], v[156:159], v[180:183], v[122:125]
	v_mfma_f32_16x16x32_bf16 v[122:125], v[160:163], v[184:187], v[122:125]
	v_mfma_f32_16x16x32_bf16 v[110:113], v[156:159], v[188:191], v[110:113]
	v_mfma_f32_16x16x32_bf16 v[110:113], v[160:163], v[192:195], v[110:113]
	v_mfma_f32_16x16x32_bf16 v[94:97], v[156:159], v[196:199], v[94:97]
	v_mfma_f32_16x16x32_bf16 v[94:97], v[160:163], v[206:209], v[94:97]
	v_mfma_f32_16x16x32_bf16 v[78:81], v[156:159], v[212:215], v[78:81]
	v_mfma_f32_16x16x32_bf16 v[78:81], v[160:163], v[220:223], v[78:81]
	s_setprio 0
	s_setprio 1
	v_mfma_f32_16x16x32_bf16 v[114:117], v[164:167], v[180:183], v[114:117]
	v_mfma_f32_16x16x32_bf16 v[114:117], v[168:171], v[184:187], v[114:117]
	v_mfma_f32_16x16x32_bf16 v[98:101], v[164:167], v[188:191], v[98:101]
	v_mfma_f32_16x16x32_bf16 v[98:101], v[168:171], v[192:195], v[98:101]
	v_mfma_f32_16x16x32_bf16 v[82:85], v[164:167], v[196:199], v[82:85]
	v_mfma_f32_16x16x32_bf16 v[82:85], v[168:171], v[206:209], v[82:85]
	v_mfma_f32_16x16x32_bf16 v[70:73], v[164:167], v[212:215], v[70:73]
	v_mfma_f32_16x16x32_bf16 v[70:73], v[168:171], v[220:223], v[70:73]
	v_mfma_f32_16x16x32_bf16 v[106:109], v[172:175], v[180:183], v[106:109]
	v_mfma_f32_16x16x32_bf16 v[106:109], v[176:179], v[184:187], v[106:109]
	v_mfma_f32_16x16x32_bf16 v[90:93], v[172:175], v[188:191], v[90:93]
	v_mfma_f32_16x16x32_bf16 v[90:93], v[176:179], v[192:195], v[90:93]
	v_mfma_f32_16x16x32_bf16 v[74:77], v[172:175], v[196:199], v[74:77]
	v_mfma_f32_16x16x32_bf16 v[74:77], v[176:179], v[206:209], v[74:77]
	v_mfma_f32_16x16x32_bf16 v[66:69], v[172:175], v[212:215], v[66:69]
	v_mfma_f32_16x16x32_bf16 v[66:69], v[176:179], v[220:223], v[66:69]
	s_barrier
	s_setprio 0
	s_mov_b32 m0, s31
	s_add_u32 s40, s16, 0x4000
	ds_read_b128 v[180:183], v145 offset:16384
	ds_read_b128 v[184:187], v145 offset:17408
	ds_read_b128 v[188:191], v145 offset:18432
	ds_read_b128 v[192:195], v145 offset:19456
	ds_read_b128 v[196:199], v145 offset:20480
	ds_read_b128 v[206:209], v145 offset:21504
	ds_read_b128 v[212:215], v145 offset:22528
	ds_read_b128 v[220:223], v145 offset:23552
	global_load_lds_dwordx4 v134, s[16:17]
	s_mov_b32 m0, s33
	s_addc_u32 s41, s17, 0
	global_load_lds_dwordx4 v130, s[16:17]
	s_mov_b32 m0, s34
	s_nop 0
	global_load_lds_dwordx4 v134, s[40:41]
	s_mov_b32 m0, s35
	s_nop 0
	global_load_lds_dwordx4 v130, s[40:41]
	s_mov_b32 m0, s1
	s_nop 0
	global_load_lds_dwordx4 v136, s[18:19]
	s_mov_b32 m0, s3
	s_nop 0
	global_load_lds_dwordx4 v132, s[18:19]
	s_waitcnt vmcnt(8)
	s_waitcnt lgkmcnt(0)
	s_setprio 1
	s_barrier
	v_mfma_f32_16x16x32_bf16 v[62:65], v[148:151], v[180:183], v[62:65]
	v_mfma_f32_16x16x32_bf16 v[62:65], v[152:155], v[184:187], v[62:65]
	v_mfma_f32_16x16x32_bf16 v[54:57], v[148:151], v[188:191], v[54:57]
	v_mfma_f32_16x16x32_bf16 v[54:57], v[152:155], v[192:195], v[54:57]
	v_mfma_f32_16x16x32_bf16 v[38:41], v[148:151], v[196:199], v[38:41]
	v_mfma_f32_16x16x32_bf16 v[38:41], v[152:155], v[206:209], v[38:41]
	v_mfma_f32_16x16x32_bf16 v[22:25], v[148:151], v[212:215], v[22:25]
	v_mfma_f32_16x16x32_bf16 v[22:25], v[152:155], v[220:223], v[22:25]
	v_mfma_f32_16x16x32_bf16 v[58:61], v[156:159], v[180:183], v[58:61]
	v_mfma_f32_16x16x32_bf16 v[58:61], v[160:163], v[184:187], v[58:61]
	v_mfma_f32_16x16x32_bf16 v[46:49], v[156:159], v[188:191], v[46:49]
	v_mfma_f32_16x16x32_bf16 v[46:49], v[160:163], v[192:195], v[46:49]
	v_mfma_f32_16x16x32_bf16 v[30:33], v[156:159], v[196:199], v[30:33]
	v_mfma_f32_16x16x32_bf16 v[30:33], v[160:163], v[206:209], v[30:33]
	v_mfma_f32_16x16x32_bf16 v[14:17], v[156:159], v[212:215], v[14:17]
	v_mfma_f32_16x16x32_bf16 v[14:17], v[160:163], v[220:223], v[14:17]
	s_setprio 0
	s_setprio 1
	v_mfma_f32_16x16x32_bf16 v[50:53], v[164:167], v[180:183], v[50:53]
	v_mfma_f32_16x16x32_bf16 v[50:53], v[168:171], v[184:187], v[50:53]
	v_mfma_f32_16x16x32_bf16 v[34:37], v[164:167], v[188:191], v[34:37]
	v_mfma_f32_16x16x32_bf16 v[34:37], v[168:171], v[192:195], v[34:37]
	v_mfma_f32_16x16x32_bf16 v[18:21], v[164:167], v[196:199], v[18:21]
	v_mfma_f32_16x16x32_bf16 v[18:21], v[168:171], v[206:209], v[18:21]
	v_mfma_f32_16x16x32_bf16 v[6:9], v[164:167], v[212:215], v[6:9]
	v_mfma_f32_16x16x32_bf16 v[6:9], v[168:171], v[220:223], v[6:9]
	v_mfma_f32_16x16x32_bf16 v[42:45], v[172:175], v[180:183], v[42:45]
	v_mfma_f32_16x16x32_bf16 v[42:45], v[176:179], v[184:187], v[42:45]
	v_mfma_f32_16x16x32_bf16 v[26:29], v[172:175], v[188:191], v[26:29]
	v_mfma_f32_16x16x32_bf16 v[26:29], v[176:179], v[192:195], v[26:29]
	v_mfma_f32_16x16x32_bf16 v[10:13], v[172:175], v[196:199], v[10:13]
	v_mfma_f32_16x16x32_bf16 v[10:13], v[176:179], v[206:209], v[10:13]
	v_mfma_f32_16x16x32_bf16 v[2:5], v[172:175], v[212:215], v[2:5]
	v_mfma_f32_16x16x32_bf16 v[2:5], v[176:179], v[220:223], v[2:5]
	s_barrier
	s_setprio 0
	ds_read_b128 v[148:151], v146
	ds_read_b128 v[152:155], v146 offset:1024
	ds_read_b128 v[156:159], v146 offset:2048
	ds_read_b128 v[160:163], v146 offset:3072
	ds_read_b128 v[164:167], v147
	ds_read_b128 v[168:171], v147 offset:1024
	ds_read_b128 v[172:175], v147 offset:2048
	ds_read_b128 v[176:179], v147 offset:3072
	s_add_u32 s18, s18, 0x4000
	s_addc_u32 s19, s19, 0
	s_mov_b32 m0, s20
	ds_read_b128 v[180:183], v145 offset:32768
	ds_read_b128 v[184:187], v145 offset:33792
	ds_read_b128 v[188:191], v145 offset:34816
	ds_read_b128 v[192:195], v145 offset:35840
	ds_read_b128 v[196:199], v145 offset:36864
	ds_read_b128 v[206:209], v145 offset:37888
	ds_read_b128 v[212:215], v145 offset:38912
	ds_read_b128 v[220:223], v145 offset:39936
	global_load_lds_dwordx4 v136, s[18:19]
	s_mov_b32 m0, s21
	s_nop 0
	global_load_lds_dwordx4 v132, s[18:19]
	s_waitcnt vmcnt(8)
	s_waitcnt lgkmcnt(0)
	s_setprio 1
	s_barrier
	v_mfma_f32_16x16x32_bf16 v[126:129], v[148:151], v[180:183], v[126:129]
	v_mfma_f32_16x16x32_bf16 v[126:129], v[152:155], v[184:187], v[126:129]
	v_mfma_f32_16x16x32_bf16 v[118:121], v[148:151], v[188:191], v[118:121]
	v_mfma_f32_16x16x32_bf16 v[118:121], v[152:155], v[192:195], v[118:121]
	v_mfma_f32_16x16x32_bf16 v[102:105], v[148:151], v[196:199], v[102:105]
	v_mfma_f32_16x16x32_bf16 v[102:105], v[152:155], v[206:209], v[102:105]
	v_mfma_f32_16x16x32_bf16 v[86:89], v[148:151], v[212:215], v[86:89]
	v_mfma_f32_16x16x32_bf16 v[86:89], v[152:155], v[220:223], v[86:89]
	v_mfma_f32_16x16x32_bf16 v[122:125], v[156:159], v[180:183], v[122:125]
	v_mfma_f32_16x16x32_bf16 v[122:125], v[160:163], v[184:187], v[122:125]
	v_mfma_f32_16x16x32_bf16 v[110:113], v[156:159], v[188:191], v[110:113]
	v_mfma_f32_16x16x32_bf16 v[110:113], v[160:163], v[192:195], v[110:113]
	v_mfma_f32_16x16x32_bf16 v[94:97], v[156:159], v[196:199], v[94:97]
	v_mfma_f32_16x16x32_bf16 v[94:97], v[160:163], v[206:209], v[94:97]
	v_mfma_f32_16x16x32_bf16 v[78:81], v[156:159], v[212:215], v[78:81]
	v_mfma_f32_16x16x32_bf16 v[78:81], v[160:163], v[220:223], v[78:81]
	s_setprio 0
	s_setprio 1
	v_mfma_f32_16x16x32_bf16 v[114:117], v[164:167], v[180:183], v[114:117]
	v_mfma_f32_16x16x32_bf16 v[114:117], v[168:171], v[184:187], v[114:117]
	v_mfma_f32_16x16x32_bf16 v[98:101], v[164:167], v[188:191], v[98:101]
	v_mfma_f32_16x16x32_bf16 v[98:101], v[168:171], v[192:195], v[98:101]
	v_mfma_f32_16x16x32_bf16 v[82:85], v[164:167], v[196:199], v[82:85]
	v_mfma_f32_16x16x32_bf16 v[82:85], v[168:171], v[206:209], v[82:85]
	v_mfma_f32_16x16x32_bf16 v[70:73], v[164:167], v[212:215], v[70:73]
	v_mfma_f32_16x16x32_bf16 v[70:73], v[168:171], v[220:223], v[70:73]
	v_mfma_f32_16x16x32_bf16 v[106:109], v[172:175], v[180:183], v[106:109]
	v_mfma_f32_16x16x32_bf16 v[106:109], v[176:179], v[184:187], v[106:109]
	v_mfma_f32_16x16x32_bf16 v[90:93], v[172:175], v[188:191], v[90:93]
	v_mfma_f32_16x16x32_bf16 v[90:93], v[176:179], v[192:195], v[90:93]
	v_mfma_f32_16x16x32_bf16 v[74:77], v[172:175], v[196:199], v[74:77]
	v_mfma_f32_16x16x32_bf16 v[74:77], v[176:179], v[206:209], v[74:77]
	v_mfma_f32_16x16x32_bf16 v[66:69], v[172:175], v[212:215], v[66:69]
	v_mfma_f32_16x16x32_bf16 v[66:69], v[176:179], v[220:223], v[66:69]
	s_barrier
	s_setprio 0
	s_add_u32 s18, s16, 0x20000
	s_addc_u32 s19, s17, 0
	s_mov_b32 m0, s36
	s_add_u32 s16, s16, 0x24000
	ds_read_b128 v[180:183], v145 offset:49152
	ds_read_b128 v[184:187], v145 offset:50176
	ds_read_b128 v[188:191], v145 offset:51200
	ds_read_b128 v[192:195], v145 offset:52224
	ds_read_b128 v[196:199], v145 offset:53248
	ds_read_b128 v[206:209], v145 offset:54272
	ds_read_b128 v[212:215], v145 offset:55296
	ds_read_b128 v[220:223], v145 offset:56320
	global_load_lds_dwordx4 v134, s[18:19]
	s_mov_b32 m0, s37
	s_addc_u32 s17, s17, 0
	global_load_lds_dwordx4 v130, s[18:19]
	s_mov_b32 m0, s38
	s_nop 0
	global_load_lds_dwordx4 v134, s[16:17]
	s_mov_b32 m0, s39
	s_nop 0
	global_load_lds_dwordx4 v130, s[16:17]
	s_mov_b32 m0, s24
	s_nop 0
	global_load_lds_dwordx4 v136, s[10:11]
	s_mov_b32 m0, s25
	s_nop 0
	global_load_lds_dwordx4 v132, s[10:11]
	s_waitcnt vmcnt(8)
	s_waitcnt lgkmcnt(0)
	s_setprio 1
	s_barrier
	v_mfma_f32_16x16x32_bf16 v[62:65], v[148:151], v[180:183], v[62:65]
	v_mfma_f32_16x16x32_bf16 v[62:65], v[152:155], v[184:187], v[62:65]
	v_mfma_f32_16x16x32_bf16 v[54:57], v[148:151], v[188:191], v[54:57]
	v_mfma_f32_16x16x32_bf16 v[54:57], v[152:155], v[192:195], v[54:57]
	v_mfma_f32_16x16x32_bf16 v[38:41], v[148:151], v[196:199], v[38:41]
	v_mfma_f32_16x16x32_bf16 v[38:41], v[152:155], v[206:209], v[38:41]
	v_mfma_f32_16x16x32_bf16 v[22:25], v[148:151], v[212:215], v[22:25]
	v_mfma_f32_16x16x32_bf16 v[22:25], v[152:155], v[220:223], v[22:25]
	v_mfma_f32_16x16x32_bf16 v[58:61], v[156:159], v[180:183], v[58:61]
	v_mfma_f32_16x16x32_bf16 v[58:61], v[160:163], v[184:187], v[58:61]
	v_mfma_f32_16x16x32_bf16 v[46:49], v[156:159], v[188:191], v[46:49]
	v_mfma_f32_16x16x32_bf16 v[46:49], v[160:163], v[192:195], v[46:49]
	v_mfma_f32_16x16x32_bf16 v[30:33], v[156:159], v[196:199], v[30:33]
	v_mfma_f32_16x16x32_bf16 v[30:33], v[160:163], v[206:209], v[30:33]
	v_mfma_f32_16x16x32_bf16 v[14:17], v[156:159], v[212:215], v[14:17]
	v_mfma_f32_16x16x32_bf16 v[14:17], v[160:163], v[220:223], v[14:17]
	s_setprio 0
	s_setprio 1
	v_mfma_f32_16x16x32_bf16 v[50:53], v[164:167], v[180:183], v[50:53]
	v_mfma_f32_16x16x32_bf16 v[50:53], v[168:171], v[184:187], v[50:53]
	v_mfma_f32_16x16x32_bf16 v[34:37], v[164:167], v[188:191], v[34:37]
	v_mfma_f32_16x16x32_bf16 v[34:37], v[168:171], v[192:195], v[34:37]
	v_mfma_f32_16x16x32_bf16 v[18:21], v[164:167], v[196:199], v[18:21]
	v_mfma_f32_16x16x32_bf16 v[18:21], v[168:171], v[206:209], v[18:21]
	v_mfma_f32_16x16x32_bf16 v[6:9], v[164:167], v[212:215], v[6:9]
	v_mfma_f32_16x16x32_bf16 v[6:9], v[168:171], v[220:223], v[6:9]
	v_mfma_f32_16x16x32_bf16 v[42:45], v[172:175], v[180:183], v[42:45]
	v_mfma_f32_16x16x32_bf16 v[42:45], v[176:179], v[184:187], v[42:45]
	v_mfma_f32_16x16x32_bf16 v[26:29], v[172:175], v[188:191], v[26:29]
	v_mfma_f32_16x16x32_bf16 v[26:29], v[176:179], v[192:195], v[26:29]
	v_mfma_f32_16x16x32_bf16 v[10:13], v[172:175], v[196:199], v[10:13]
	v_mfma_f32_16x16x32_bf16 v[10:13], v[176:179], v[206:209], v[10:13]
	v_mfma_f32_16x16x32_bf16 v[2:5], v[172:175], v[212:215], v[2:5]
	v_mfma_f32_16x16x32_bf16 v[2:5], v[176:179], v[220:223], v[2:5]
	s_barrier
	s_setprio 0
	s_add_i32 s28, s28, 2
	s_add_u32 s26, s26, 0x40000
	s_addc_u32 s27, s27, 0
	s_add_u32 s6, s6, 0x10000
	s_addc_u32 s7, s7, 0
	s_cmp_gt_u32 s28, 61
	s_cbranch_scc0 .LBB0_1670
	s_lshl_b32 s1, s2, 8
	v_and_or_b32 v132, v142, 15, s22
	v_lshrrev_b32_e32 v130, 1, v142
	v_and_or_b32 v130, v130, 24, s1
	v_ashrrev_i32_e32 v133, 31, v132
	v_or_b32_e32 v134, s23, v130
	v_lshlrev_b64 v[130:131], 11, v[132:133]
	v_lshl_add_u64 v[130:131], s[8:9], 0, v[130:131]
	v_lshlrev_b32_e32 v134, 1, v134
	v_mov_b32_e32 v135, 0
	v_lshl_add_u64 v[130:131], v[130:131], 0, v[134:135]
	v_cvt_pk_bf16_f32 v126, v126, v127
	v_cvt_pk_bf16_f32 v127, v128, v129
	v_cvt_pk_bf16_f32 v128, v122, v123
	v_cvt_pk_bf16_f32 v129, v124, v125
	global_store_dwordx4 v[130:131], v[126:129], off
	v_cvt_pk_bf16_f32 v114, v114, v115
	v_cvt_pk_bf16_f32 v115, v116, v117
	v_cvt_pk_bf16_f32 v116, v106, v107
	v_or_b32_e32 v106, 16, v132
	v_ashrrev_i32_e32 v107, 31, v106
	v_lshlrev_b64 v[106:107], 11, v[106:107]
	v_lshl_add_u64 v[106:107], s[8:9], 0, v[106:107]
	v_cvt_pk_bf16_f32 v117, v108, v109
	global_store_dwordx4 v[130:131], v[114:117], off offset:256
	s_mov_b32 s1, 0x40000
	s_mov_b64 s[2:3], 0x40000
	v_lshl_add_u64 v[114:115], v[106:107], 0, v[134:135]
	v_cvt_pk_bf16_f32 v106, v118, v119
	v_cvt_pk_bf16_f32 v107, v120, v121
	v_cvt_pk_bf16_f32 v108, v110, v111
	v_cvt_pk_bf16_f32 v109, v112, v113
	global_store_dwordx4 v[114:115], v[106:109], off
	v_cvt_pk_bf16_f32 v98, v98, v99
	v_cvt_pk_bf16_f32 v99, v100, v101
	v_cvt_pk_bf16_f32 v100, v90, v91
	v_or_b32_e32 v90, 32, v132
	v_ashrrev_i32_e32 v91, 31, v90
	v_lshlrev_b64 v[90:91], 11, v[90:91]
	v_lshl_add_u64 v[90:91], s[8:9], 0, v[90:91]
	v_cvt_pk_bf16_f32 v101, v92, v93
	global_store_dwordx4 v[114:115], v[98:101], off offset:256
	s_cmpk_lt_u32 s0, 0x100
	s_nop 0
	v_lshl_add_u64 v[98:99], v[90:91], 0, v[134:135]
	v_cvt_pk_bf16_f32 v90, v102, v103
	v_cvt_pk_bf16_f32 v91, v104, v105
	v_cvt_pk_bf16_f32 v92, v94, v95
	v_cvt_pk_bf16_f32 v93, v96, v97
	global_store_dwordx4 v[98:99], v[90:93], off
	v_cvt_pk_bf16_f32 v82, v82, v83
	v_cvt_pk_bf16_f32 v83, v84, v85
	v_cvt_pk_bf16_f32 v84, v74, v75
	v_or_b32_e32 v74, 48, v132
	v_ashrrev_i32_e32 v75, 31, v74
	v_lshlrev_b64 v[74:75], 11, v[74:75]
	v_lshl_add_u64 v[74:75], s[8:9], 0, v[74:75]
	v_cvt_pk_bf16_f32 v85, v76, v77
	global_store_dwordx4 v[98:99], v[82:85], off offset:256
	s_nop 1
	v_lshl_add_u64 v[82:83], v[74:75], 0, v[134:135]
	v_cvt_pk_bf16_f32 v74, v86, v87
	v_cvt_pk_bf16_f32 v75, v88, v89
	v_cvt_pk_bf16_f32 v76, v78, v79
	v_cvt_pk_bf16_f32 v77, v80, v81
	global_store_dwordx4 v[82:83], v[74:77], off
	v_cvt_pk_bf16_f32 v70, v70, v71
	v_cvt_pk_bf16_f32 v71, v72, v73
	v_cvt_pk_bf16_f32 v72, v66, v67
	v_cvt_pk_bf16_f32 v73, v68, v69
	global_store_dwordx4 v[82:83], v[70:73], off offset:256
	v_cvt_pk_bf16_f32 v62, v62, v63
	v_cvt_pk_bf16_f32 v63, v64, v65
	v_cvt_pk_bf16_f32 v64, v58, v59
	v_add_co_u32_e32 v58, vcc, s1, v130
	v_lshl_add_u64 v[66:67], v[130:131], 0, s[2:3]
	s_nop 0
	v_addc_co_u32_e32 v59, vcc, 0, v131, vcc
	s_mov_b32 s1, 0x48000
	v_cvt_pk_bf16_f32 v65, v60, v61
	global_store_dwordx4 v[58:59], v[62:65], off
	v_cvt_pk_bf16_f32 v50, v50, v51
	v_cvt_pk_bf16_f32 v51, v52, v53
	v_cvt_pk_bf16_f32 v52, v42, v43
	v_cvt_pk_bf16_f32 v53, v44, v45
	global_store_dwordx4 v[66:67], v[50:53], off offset:256
	s_mov_b64 s[2:3], 0x48000
	v_cvt_pk_bf16_f32 v42, v54, v55
	v_cvt_pk_bf16_f32 v43, v56, v57
	v_cvt_pk_bf16_f32 v44, v46, v47
	v_add_co_u32_e32 v46, vcc, s1, v130
	v_lshl_add_u64 v[50:51], v[130:131], 0, s[2:3]
	s_nop 0
	v_addc_co_u32_e32 v47, vcc, 0, v131, vcc
	s_mov_b32 s1, 0x50000
	v_cvt_pk_bf16_f32 v45, v48, v49
	global_store_dwordx4 v[46:47], v[42:45], off
	v_cvt_pk_bf16_f32 v34, v34, v35
	v_cvt_pk_bf16_f32 v35, v36, v37
	v_cvt_pk_bf16_f32 v36, v26, v27
	v_cvt_pk_bf16_f32 v37, v28, v29
	global_store_dwordx4 v[50:51], v[34:37], off offset:256
	s_mov_b64 s[2:3], 0x50000
	v_cvt_pk_bf16_f32 v26, v38, v39
	v_cvt_pk_bf16_f32 v27, v40, v41
	v_cvt_pk_bf16_f32 v28, v30, v31
	v_add_co_u32_e32 v30, vcc, s1, v130
	v_lshl_add_u64 v[34:35], v[130:131], 0, s[2:3]
	s_nop 0
	v_addc_co_u32_e32 v31, vcc, 0, v131, vcc
	s_mov_b32 s1, 0x58000
	v_cvt_pk_bf16_f32 v29, v32, v33
	global_store_dwordx4 v[30:31], v[26:29], off
	v_cvt_pk_bf16_f32 v18, v18, v19
	v_cvt_pk_bf16_f32 v19, v20, v21
	v_cvt_pk_bf16_f32 v20, v10, v11
	v_cvt_pk_bf16_f32 v21, v12, v13
	global_store_dwordx4 v[34:35], v[18:21], off offset:256
	s_mov_b64 s[2:3], 0x58000
	v_cvt_pk_bf16_f32 v10, v22, v23
	v_cvt_pk_bf16_f32 v11, v24, v25
	v_cvt_pk_bf16_f32 v12, v14, v15
	v_add_co_u32_e32 v14, vcc, s1, v130
	v_lshl_add_u64 v[18:19], v[130:131], 0, s[2:3]
	s_nop 0
	v_addc_co_u32_e32 v15, vcc, 0, v131, vcc
	v_cvt_pk_bf16_f32 v13, v16, v17
	global_store_dwordx4 v[14:15], v[10:13], off
	v_cvt_pk_bf16_f32 v6, v6, v7
	v_cvt_pk_bf16_f32 v7, v8, v9
	v_cvt_pk_bf16_f32 v8, v2, v3
	v_cvt_pk_bf16_f32 v9, v4, v5
	global_store_dwordx4 v[18:19], v[6:9], off offset:256
	s_waitcnt vmcnt(0)
	s_cbranch_scc0 .LBB0_1673
	s_barrier

.LBB0_1691:
	ds_read_b128 v[142:145], v150
	ds_read_b128 v[154:157], v150 offset:1024
	ds_read_b128 v[158:161], v150 offset:2048
	ds_read_b128 v[162:165], v150 offset:3072
	ds_read_b128 v[166:169], v151
	ds_read_b128 v[170:173], v151 offset:1024
	ds_read_b128 v[174:177], v151 offset:2048
	ds_read_b128 v[178:181], v151 offset:3072
	s_add_u32 s24, s22, 0xfc000
	s_addc_u32 s25, s23, 0
	s_cmp_eq_u32 s46, 60
	s_cselect_b32 s28, s17, s24
	s_cselect_b32 s29, s11, s25
	s_cselect_b32 s26, s43, s44
	s_cselect_b32 s27, s7, s45
	s_add_u32 s24, s28, 0x100000
	s_addc_u32 s25, s29, 0
	s_add_i32 m0, s30, 0xc000
	ds_read_b128 v[182:185], v152
	ds_read_b128 v[186:189], v152 offset:1024
	ds_read_b128 v[190:193], v152 offset:2048
	ds_read_b128 v[194:197], v152 offset:3072
	ds_read_b128 v[206:209], v152 offset:4096
	ds_read_b128 v[212:215], v152 offset:5120
	ds_read_b128 v[220:223], v152 offset:6144
	ds_read_b128 v[224:227], v152 offset:7168
	global_load_lds_dwordx4 v138, s[22:23]
	s_add_i32 m0, s30, 0xe000
	s_nop 0
	global_load_lds_dwordx4 v140, s[22:23]
	s_waitcnt vmcnt(8)
	s_waitcnt lgkmcnt(0)
	s_setprio 1
	s_barrier
	v_mfma_f32_16x16x32_bf16 v[126:129], v[142:145], v[182:185], v[126:129]
	v_mfma_f32_16x16x32_bf16 v[126:129], v[154:157], v[186:189], v[126:129]
	v_mfma_f32_16x16x32_bf16 v[110:113], v[142:145], v[190:193], v[110:113]
	v_mfma_f32_16x16x32_bf16 v[110:113], v[154:157], v[194:197], v[110:113]
	v_mfma_f32_16x16x32_bf16 v[94:97], v[142:145], v[206:209], v[94:97]
	v_mfma_f32_16x16x32_bf16 v[94:97], v[154:157], v[212:215], v[94:97]
	v_mfma_f32_16x16x32_bf16 v[78:81], v[142:145], v[220:223], v[78:81]
	v_mfma_f32_16x16x32_bf16 v[78:81], v[154:157], v[224:227], v[78:81]
	v_mfma_f32_16x16x32_bf16 v[122:125], v[158:161], v[182:185], v[122:125]
	v_mfma_f32_16x16x32_bf16 v[122:125], v[162:165], v[186:189], v[122:125]
	v_mfma_f32_16x16x32_bf16 v[106:109], v[158:161], v[190:193], v[106:109]
	v_mfma_f32_16x16x32_bf16 v[106:109], v[162:165], v[194:197], v[106:109]
	v_mfma_f32_16x16x32_bf16 v[90:93], v[158:161], v[206:209], v[90:93]
	v_mfma_f32_16x16x32_bf16 v[90:93], v[162:165], v[212:215], v[90:93]
	v_mfma_f32_16x16x32_bf16 v[74:77], v[158:161], v[220:223], v[74:77]
	v_mfma_f32_16x16x32_bf16 v[74:77], v[162:165], v[224:227], v[74:77]
	s_setprio 0
	s_setprio 1
	v_mfma_f32_16x16x32_bf16 v[118:121], v[166:169], v[182:185], v[118:121]
	v_mfma_f32_16x16x32_bf16 v[118:121], v[170:173], v[186:189], v[118:121]
	v_mfma_f32_16x16x32_bf16 v[102:105], v[166:169], v[190:193], v[102:105]
	v_mfma_f32_16x16x32_bf16 v[102:105], v[170:173], v[194:197], v[102:105]
	v_mfma_f32_16x16x32_bf16 v[86:89], v[166:169], v[206:209], v[86:89]
	v_mfma_f32_16x16x32_bf16 v[86:89], v[170:173], v[212:215], v[86:89]
	v_mfma_f32_16x16x32_bf16 v[70:73], v[166:169], v[220:223], v[70:73]
	v_mfma_f32_16x16x32_bf16 v[70:73], v[170:173], v[224:227], v[70:73]
	v_mfma_f32_16x16x32_bf16 v[114:117], v[174:177], v[182:185], v[114:117]
	v_mfma_f32_16x16x32_bf16 v[114:117], v[178:181], v[186:189], v[114:117]
	v_mfma_f32_16x16x32_bf16 v[98:101], v[174:177], v[190:193], v[98:101]
	v_mfma_f32_16x16x32_bf16 v[98:101], v[178:181], v[194:197], v[98:101]
	v_mfma_f32_16x16x32_bf16 v[82:85], v[174:177], v[206:209], v[82:85]
	v_mfma_f32_16x16x32_bf16 v[82:85], v[178:181], v[212:215], v[82:85]
	v_mfma_f32_16x16x32_bf16 v[66:69], v[174:177], v[220:223], v[66:69]
	v_mfma_f32_16x16x32_bf16 v[66:69], v[178:181], v[224:227], v[66:69]
	s_barrier
	s_setprio 0
	s_add_i32 s47, s40, s1
	s_mov_b32 m0, s47
	ds_read_b128 v[182:185], v152 offset:16384
	ds_read_b128 v[186:189], v152 offset:17408
	ds_read_b128 v[190:193], v152 offset:18432
	ds_read_b128 v[194:197], v152 offset:19456
	ds_read_b128 v[206:209], v152 offset:20480
	ds_read_b128 v[212:215], v152 offset:21504
	ds_read_b128 v[220:223], v152 offset:22528
	ds_read_b128 v[224:227], v152 offset:23552
	global_load_lds_dwordx4 v132, s[26:27]
	s_add_i32 m0, s47, 0x2000
	s_add_u32 s48, s26, 0x4000
	s_addc_u32 s49, s27, 0
	s_add_i32 s47, s41, s1
	global_load_lds_dwordx4 v136, s[26:27]
	s_mov_b32 m0, s47
	s_nop 0
	global_load_lds_dwordx4 v132, s[48:49]
	s_add_i32 m0, s47, 0x2000
	s_nop 0
	global_load_lds_dwordx4 v136, s[48:49]
	s_mov_b32 m0, s30
	s_nop 0
	global_load_lds_dwordx4 v130, s[28:29]
	s_mov_b32 m0, s31
	s_nop 0
	global_load_lds_dwordx4 v134, s[28:29]
	s_waitcnt vmcnt(8)
	s_waitcnt lgkmcnt(0)
	s_setprio 1
	s_barrier
	v_mfma_f32_16x16x32_bf16 v[62:65], v[142:145], v[182:185], v[62:65]
	v_mfma_f32_16x16x32_bf16 v[62:65], v[154:157], v[186:189], v[62:65]
	v_mfma_f32_16x16x32_bf16 v[46:49], v[142:145], v[190:193], v[46:49]
	v_mfma_f32_16x16x32_bf16 v[46:49], v[154:157], v[194:197], v[46:49]
	v_mfma_f32_16x16x32_bf16 v[30:33], v[142:145], v[206:209], v[30:33]
	v_mfma_f32_16x16x32_bf16 v[30:33], v[154:157], v[212:215], v[30:33]
	v_mfma_f32_16x16x32_bf16 v[14:17], v[142:145], v[220:223], v[14:17]
	v_mfma_f32_16x16x32_bf16 v[14:17], v[154:157], v[224:227], v[14:17]
	v_mfma_f32_16x16x32_bf16 v[58:61], v[158:161], v[182:185], v[58:61]
	v_mfma_f32_16x16x32_bf16 v[58:61], v[162:165], v[186:189], v[58:61]
	v_mfma_f32_16x16x32_bf16 v[42:45], v[158:161], v[190:193], v[42:45]
	v_mfma_f32_16x16x32_bf16 v[42:45], v[162:165], v[194:197], v[42:45]
	v_mfma_f32_16x16x32_bf16 v[26:29], v[158:161], v[206:209], v[26:29]
	v_mfma_f32_16x16x32_bf16 v[26:29], v[162:165], v[212:215], v[26:29]
	v_mfma_f32_16x16x32_bf16 v[10:13], v[158:161], v[220:223], v[10:13]
	v_mfma_f32_16x16x32_bf16 v[10:13], v[162:165], v[224:227], v[10:13]
	s_setprio 0
	s_setprio 1
	v_mfma_f32_16x16x32_bf16 v[54:57], v[166:169], v[182:185], v[54:57]
	v_mfma_f32_16x16x32_bf16 v[54:57], v[170:173], v[186:189], v[54:57]
	v_mfma_f32_16x16x32_bf16 v[38:41], v[166:169], v[190:193], v[38:41]
	v_mfma_f32_16x16x32_bf16 v[38:41], v[170:173], v[194:197], v[38:41]
	v_mfma_f32_16x16x32_bf16 v[22:25], v[166:169], v[206:209], v[22:25]
	v_mfma_f32_16x16x32_bf16 v[22:25], v[170:173], v[212:215], v[22:25]
	v_mfma_f32_16x16x32_bf16 v[6:9], v[166:169], v[220:223], v[6:9]
	v_mfma_f32_16x16x32_bf16 v[6:9], v[170:173], v[224:227], v[6:9]
	v_mfma_f32_16x16x32_bf16 v[50:53], v[174:177], v[182:185], v[50:53]
	v_mfma_f32_16x16x32_bf16 v[50:53], v[178:181], v[186:189], v[50:53]
	v_mfma_f32_16x16x32_bf16 v[34:37], v[174:177], v[190:193], v[34:37]
	v_mfma_f32_16x16x32_bf16 v[34:37], v[178:181], v[194:197], v[34:37]
	v_mfma_f32_16x16x32_bf16 v[18:21], v[174:177], v[206:209], v[18:21]
	v_mfma_f32_16x16x32_bf16 v[18:21], v[178:181], v[212:215], v[18:21]
	v_mfma_f32_16x16x32_bf16 v[2:5], v[174:177], v[220:223], v[2:5]
	v_mfma_f32_16x16x32_bf16 v[2:5], v[178:181], v[224:227], v[2:5]
	s_barrier
	s_setprio 0
	s_add_i32 s47, 0, 0x18000
	v_add_u32_e32 v146, s47, v149
	s_add_i32 s48, 0, 0x1c000
	ds_read_b128 v[142:145], v146
	ds_read_b128 v[154:157], v146 offset:1024
	ds_read_b128 v[158:161], v146 offset:2048
	ds_read_b128 v[162:165], v146 offset:3072
	v_add_u32_e32 v146, s48, v149
	ds_read_b128 v[166:169], v146
	ds_read_b128 v[170:173], v146 offset:1024
	ds_read_b128 v[174:177], v146 offset:2048
	ds_read_b128 v[178:181], v146 offset:3072
	s_add_u32 s28, s28, 0x4000
	s_addc_u32 s29, s29, 0
	s_mov_b32 m0, s33
	ds_read_b128 v[182:185], v152 offset:32768
	ds_read_b128 v[186:189], v152 offset:33792
	ds_read_b128 v[190:193], v152 offset:34816
	ds_read_b128 v[194:197], v152 offset:35840
	ds_read_b128 v[206:209], v152 offset:36864
	ds_read_b128 v[212:215], v152 offset:37888
	ds_read_b128 v[220:223], v152 offset:38912
	ds_read_b128 v[224:227], v152 offset:39936
	global_load_lds_dwordx4 v130, s[28:29]
	s_mov_b32 m0, s34
	s_nop 0
	global_load_lds_dwordx4 v134, s[28:29]
	s_waitcnt vmcnt(8)
	s_waitcnt lgkmcnt(0)
	s_setprio 1
	s_barrier
	v_mfma_f32_16x16x32_bf16 v[126:129], v[142:145], v[182:185], v[126:129]
	v_mfma_f32_16x16x32_bf16 v[126:129], v[154:157], v[186:189], v[126:129]
	v_mfma_f32_16x16x32_bf16 v[110:113], v[142:145], v[190:193], v[110:113]
	v_mfma_f32_16x16x32_bf16 v[110:113], v[154:157], v[194:197], v[110:113]
	v_mfma_f32_16x16x32_bf16 v[94:97], v[142:145], v[206:209], v[94:97]
	v_mfma_f32_16x16x32_bf16 v[94:97], v[154:157], v[212:215], v[94:97]
	v_mfma_f32_16x16x32_bf16 v[78:81], v[142:145], v[220:223], v[78:81]
	v_mfma_f32_16x16x32_bf16 v[78:81], v[154:157], v[224:227], v[78:81]
	v_mfma_f32_16x16x32_bf16 v[122:125], v[158:161], v[182:185], v[122:125]
	v_mfma_f32_16x16x32_bf16 v[122:125], v[162:165], v[186:189], v[122:125]
	v_mfma_f32_16x16x32_bf16 v[106:109], v[158:161], v[190:193], v[106:109]
	v_mfma_f32_16x16x32_bf16 v[106:109], v[162:165], v[194:197], v[106:109]
	v_mfma_f32_16x16x32_bf16 v[90:93], v[158:161], v[206:209], v[90:93]
	v_mfma_f32_16x16x32_bf16 v[90:93], v[162:165], v[212:215], v[90:93]
	v_mfma_f32_16x16x32_bf16 v[74:77], v[158:161], v[220:223], v[74:77]
	v_mfma_f32_16x16x32_bf16 v[74:77], v[162:165], v[224:227], v[74:77]
	s_setprio 0
	s_setprio 1
	v_mfma_f32_16x16x32_bf16 v[118:121], v[166:169], v[182:185], v[118:121]
	v_mfma_f32_16x16x32_bf16 v[118:121], v[170:173], v[186:189], v[118:121]
	v_mfma_f32_16x16x32_bf16 v[102:105], v[166:169], v[190:193], v[102:105]
	v_mfma_f32_16x16x32_bf16 v[102:105], v[170:173], v[194:197], v[102:105]
	v_mfma_f32_16x16x32_bf16 v[86:89], v[166:169], v[206:209], v[86:89]
	v_mfma_f32_16x16x32_bf16 v[86:89], v[170:173], v[212:215], v[86:89]
	v_mfma_f32_16x16x32_bf16 v[70:73], v[166:169], v[220:223], v[70:73]
	v_mfma_f32_16x16x32_bf16 v[70:73], v[170:173], v[224:227], v[70:73]
	v_mfma_f32_16x16x32_bf16 v[114:117], v[174:177], v[182:185], v[114:117]
	v_mfma_f32_16x16x32_bf16 v[114:117], v[178:181], v[186:189], v[114:117]
	v_mfma_f32_16x16x32_bf16 v[98:101], v[174:177], v[190:193], v[98:101]
	v_mfma_f32_16x16x32_bf16 v[98:101], v[178:181], v[194:197], v[98:101]
	v_mfma_f32_16x16x32_bf16 v[82:85], v[174:177], v[206:209], v[82:85]
	v_mfma_f32_16x16x32_bf16 v[82:85], v[178:181], v[212:215], v[82:85]
	v_mfma_f32_16x16x32_bf16 v[66:69], v[174:177], v[220:223], v[66:69]
	v_mfma_f32_16x16x32_bf16 v[66:69], v[178:181], v[224:227], v[66:69]
	s_barrier
	s_setprio 0
	s_add_u32 s28, s26, 0x10000
	s_addc_u32 s29, s27, 0
	s_add_i32 s47, s47, s1
	s_mov_b32 m0, s47
	ds_read_b128 v[182:185], v152 offset:49152
	ds_read_b128 v[186:189], v152 offset:50176
	ds_read_b128 v[190:193], v152 offset:51200
	ds_read_b128 v[194:197], v152 offset:52224
	ds_read_b128 v[206:209], v152 offset:53248
	ds_read_b128 v[212:215], v152 offset:54272
	ds_read_b128 v[220:223], v152 offset:55296
	ds_read_b128 v[224:227], v152 offset:56320
	global_load_lds_dwordx4 v132, s[28:29]
	s_add_i32 m0, s47, 0x2000
	s_add_u32 s26, s26, 0x14000
	s_addc_u32 s27, s27, 0
	global_load_lds_dwordx4 v136, s[28:29]
	s_add_i32 s28, s48, s1
	s_mov_b32 m0, s28
	s_nop 0
	global_load_lds_dwordx4 v132, s[26:27]
	s_add_i32 m0, s28, 0x2000
	s_nop 0
	global_load_lds_dwordx4 v136, s[26:27]
	s_mov_b32 m0, s38
	s_nop 0
	global_load_lds_dwordx4 v130, s[24:25]
	s_mov_b32 m0, s39
	s_nop 0
	global_load_lds_dwordx4 v134, s[24:25]
	s_waitcnt vmcnt(8)
	s_waitcnt lgkmcnt(0)
	s_setprio 1
	s_barrier
	v_mfma_f32_16x16x32_bf16 v[62:65], v[142:145], v[182:185], v[62:65]
	v_mfma_f32_16x16x32_bf16 v[62:65], v[154:157], v[186:189], v[62:65]
	v_mfma_f32_16x16x32_bf16 v[46:49], v[142:145], v[190:193], v[46:49]
	v_mfma_f32_16x16x32_bf16 v[46:49], v[154:157], v[194:197], v[46:49]
	v_mfma_f32_16x16x32_bf16 v[30:33], v[142:145], v[206:209], v[30:33]
	v_mfma_f32_16x16x32_bf16 v[30:33], v[154:157], v[212:215], v[30:33]
	v_mfma_f32_16x16x32_bf16 v[14:17], v[142:145], v[220:223], v[14:17]
	v_mfma_f32_16x16x32_bf16 v[14:17], v[154:157], v[224:227], v[14:17]
	v_mfma_f32_16x16x32_bf16 v[58:61], v[158:161], v[182:185], v[58:61]
	v_mfma_f32_16x16x32_bf16 v[58:61], v[162:165], v[186:189], v[58:61]
	v_mfma_f32_16x16x32_bf16 v[42:45], v[158:161], v[190:193], v[42:45]
	v_mfma_f32_16x16x32_bf16 v[42:45], v[162:165], v[194:197], v[42:45]
	v_mfma_f32_16x16x32_bf16 v[26:29], v[158:161], v[206:209], v[26:29]
	v_mfma_f32_16x16x32_bf16 v[26:29], v[162:165], v[212:215], v[26:29]
	v_mfma_f32_16x16x32_bf16 v[10:13], v[158:161], v[220:223], v[10:13]
	v_mfma_f32_16x16x32_bf16 v[10:13], v[162:165], v[224:227], v[10:13]
	s_setprio 0
	s_setprio 1
	v_mfma_f32_16x16x32_bf16 v[54:57], v[166:169], v[182:185], v[54:57]
	v_mfma_f32_16x16x32_bf16 v[54:57], v[170:173], v[186:189], v[54:57]
	v_mfma_f32_16x16x32_bf16 v[38:41], v[166:169], v[190:193], v[38:41]
	v_mfma_f32_16x16x32_bf16 v[38:41], v[170:173], v[194:197], v[38:41]
	v_mfma_f32_16x16x32_bf16 v[22:25], v[166:169], v[206:209], v[22:25]
	v_mfma_f32_16x16x32_bf16 v[22:25], v[170:173], v[212:215], v[22:25]
	v_mfma_f32_16x16x32_bf16 v[6:9], v[166:169], v[220:223], v[6:9]
	v_mfma_f32_16x16x32_bf16 v[6:9], v[170:173], v[224:227], v[6:9]
	v_mfma_f32_16x16x32_bf16 v[50:53], v[174:177], v[182:185], v[50:53]
	v_mfma_f32_16x16x32_bf16 v[50:53], v[178:181], v[186:189], v[50:53]
	v_mfma_f32_16x16x32_bf16 v[34:37], v[174:177], v[190:193], v[34:37]
	v_mfma_f32_16x16x32_bf16 v[34:37], v[178:181], v[194:197], v[34:37]
	v_mfma_f32_16x16x32_bf16 v[18:21], v[174:177], v[206:209], v[18:21]
	v_mfma_f32_16x16x32_bf16 v[18:21], v[178:181], v[212:215], v[18:21]
	v_mfma_f32_16x16x32_bf16 v[2:5], v[174:177], v[220:223], v[2:5]
	v_mfma_f32_16x16x32_bf16 v[2:5], v[178:181], v[224:227], v[2:5]
	s_barrier
	s_setprio 0
	s_add_i32 s46, s46, 2
	s_add_u32 s44, s44, 0x20000
	s_addc_u32 s45, s45, 0
	s_add_u32 s22, s22, 0x200000
	s_addc_u32 s23, s23, 0
	s_cmp_gt_u32 s46, 61
	s_cbranch_scc0 .LBB0_1691
	s_lshl_b32 s7, s10, 8
	v_mov_b32_e32 v144, v147
	s_add_i32 s7, s7, s36
	v_cndmask_b32_e64 v145, 0, 1, s[2:3]
	v_and_or_b32 v142, v144, 15, s7
	v_ashrrev_i32_e32 v143, 31, v142
	v_mov_b32_e32 v146, 0x3e0293ee
	v_cmp_ne_u32_e64 s[10:11], 1, v145
	s_andn2_b64 vcc, exec, s[2:3]
	v_mov_b32_e32 v148, 0x3e0293ee
	s_cbranch_vccnz .LBB0_1694
	v_readlane_b32 s22, v245, 16
	v_readlane_b32 s23, v245, 17
	s_nop 1
	v_lshl_add_u64 v[154:155], v[142:143], 2, s[22:23]
	global_load_dword v145, v[154:155], off
	s_waitcnt vmcnt(0)
	v_mul_f32_e32 v148, 0x3e0293ee, v145

.LBB0_1718:
	ds_read_b128 v[152:155], v147
	ds_read_b128 v[156:159], v147 offset:1024
	ds_read_b128 v[160:163], v147 offset:2048
	ds_read_b128 v[164:167], v147 offset:3072
	ds_read_b128 v[168:171], v148
	ds_read_b128 v[172:175], v148 offset:1024
	ds_read_b128 v[176:179], v148 offset:2048
	ds_read_b128 v[180:183], v148 offset:3072
	s_add_u32 s18, s16, 0x4000
	s_addc_u32 s19, s17, 0
	s_cmp_eq_u32 s50, 60
	s_cselect_b32 s22, s14, s18
	s_cselect_b32 s23, s15, s19
	s_cselect_b32 s20, s47, s48
	s_cselect_b32 s21, s46, s49
	s_add_u32 s18, s22, 0x8000
	s_addc_u32 s19, s23, 0
	s_mov_b32 m0, s31
	ds_read_b128 v[184:187], v149
	ds_read_b128 v[188:191], v149 offset:1024
	ds_read_b128 v[192:195], v149 offset:2048
	ds_read_b128 v[196:199], v149 offset:3072
	ds_read_b128 v[206:209], v149 offset:4096
	ds_read_b128 v[212:215], v149 offset:5120
	ds_read_b128 v[220:223], v149 offset:6144
	ds_read_b128 v[224:227], v149 offset:7168
	global_load_lds_dwordx4 v140, s[16:17]
	s_mov_b32 m0, s33
	s_nop 0
	global_load_lds_dwordx4 v142, s[16:17]
	s_waitcnt vmcnt(8)
	s_waitcnt lgkmcnt(0)
	s_setprio 1
	s_barrier
	v_mfma_f32_16x16x32_bf16 v[126:129], v[152:155], v[184:187], v[126:129]
	v_mfma_f32_16x16x32_bf16 v[126:129], v[156:159], v[188:191], v[126:129]
	v_mfma_f32_16x16x32_bf16 v[118:121], v[152:155], v[192:195], v[118:121]
	v_mfma_f32_16x16x32_bf16 v[118:121], v[156:159], v[196:199], v[118:121]
	v_mfma_f32_16x16x32_bf16 v[102:105], v[152:155], v[206:209], v[102:105]
	v_mfma_f32_16x16x32_bf16 v[102:105], v[156:159], v[212:215], v[102:105]
	v_mfma_f32_16x16x32_bf16 v[86:89], v[152:155], v[220:223], v[86:89]
	v_mfma_f32_16x16x32_bf16 v[86:89], v[156:159], v[224:227], v[86:89]
	v_mfma_f32_16x16x32_bf16 v[122:125], v[160:163], v[184:187], v[122:125]
	v_mfma_f32_16x16x32_bf16 v[122:125], v[164:167], v[188:191], v[122:125]
	v_mfma_f32_16x16x32_bf16 v[110:113], v[160:163], v[192:195], v[110:113]
	v_mfma_f32_16x16x32_bf16 v[110:113], v[164:167], v[196:199], v[110:113]
	v_mfma_f32_16x16x32_bf16 v[94:97], v[160:163], v[206:209], v[94:97]
	v_mfma_f32_16x16x32_bf16 v[94:97], v[164:167], v[212:215], v[94:97]
	v_mfma_f32_16x16x32_bf16 v[78:81], v[160:163], v[220:223], v[78:81]
	v_mfma_f32_16x16x32_bf16 v[78:81], v[164:167], v[224:227], v[78:81]
	s_setprio 0
	s_setprio 1
	v_mfma_f32_16x16x32_bf16 v[114:117], v[168:171], v[184:187], v[114:117]
	v_mfma_f32_16x16x32_bf16 v[114:117], v[172:175], v[188:191], v[114:117]
	v_mfma_f32_16x16x32_bf16 v[98:101], v[168:171], v[192:195], v[98:101]
	v_mfma_f32_16x16x32_bf16 v[98:101], v[172:175], v[196:199], v[98:101]
	v_mfma_f32_16x16x32_bf16 v[82:85], v[168:171], v[206:209], v[82:85]
	v_mfma_f32_16x16x32_bf16 v[82:85], v[172:175], v[212:215], v[82:85]
	v_mfma_f32_16x16x32_bf16 v[70:73], v[168:171], v[220:223], v[70:73]
	v_mfma_f32_16x16x32_bf16 v[70:73], v[172:175], v[224:227], v[70:73]
	v_mfma_f32_16x16x32_bf16 v[106:109], v[176:179], v[184:187], v[106:109]
	v_mfma_f32_16x16x32_bf16 v[106:109], v[180:183], v[188:191], v[106:109]
	v_mfma_f32_16x16x32_bf16 v[90:93], v[176:179], v[192:195], v[90:93]
	v_mfma_f32_16x16x32_bf16 v[90:93], v[180:183], v[196:199], v[90:93]
	v_mfma_f32_16x16x32_bf16 v[74:77], v[176:179], v[206:209], v[74:77]
	v_mfma_f32_16x16x32_bf16 v[74:77], v[180:183], v[212:215], v[74:77]
	v_mfma_f32_16x16x32_bf16 v[66:69], v[176:179], v[220:223], v[66:69]
	v_mfma_f32_16x16x32_bf16 v[66:69], v[180:183], v[224:227], v[66:69]
	s_barrier
	s_setprio 0
	s_mov_b32 m0, s36
	s_add_u32 s52, s20, 0x4000
	ds_read_b128 v[184:187], v149 offset:16384
	ds_read_b128 v[188:191], v149 offset:17408
	ds_read_b128 v[192:195], v149 offset:18432
	ds_read_b128 v[196:199], v149 offset:19456
	ds_read_b128 v[206:209], v149 offset:20480
	ds_read_b128 v[212:215], v149 offset:21504
	ds_read_b128 v[220:223], v149 offset:22528
	ds_read_b128 v[224:227], v149 offset:23552
	global_load_lds_dwordx4 v134, s[20:21]
	s_mov_b32 m0, s37
	s_addc_u32 s53, s21, 0
	global_load_lds_dwordx4 v130, s[20:21]
	s_mov_b32 m0, s38
	s_nop 0
	global_load_lds_dwordx4 v134, s[52:53]
	s_mov_b32 m0, s39
	s_nop 0
	global_load_lds_dwordx4 v130, s[52:53]
	s_mov_b32 m0, s1
	s_nop 0
	global_load_lds_dwordx4 v136, s[22:23]
	s_mov_b32 m0, s24
	s_nop 0
	global_load_lds_dwordx4 v132, s[22:23]
	s_waitcnt vmcnt(8)
	s_waitcnt lgkmcnt(0)
	s_setprio 1
	s_barrier
	v_mfma_f32_16x16x32_bf16 v[62:65], v[152:155], v[184:187], v[62:65]
	v_mfma_f32_16x16x32_bf16 v[62:65], v[156:159], v[188:191], v[62:65]
	v_mfma_f32_16x16x32_bf16 v[54:57], v[152:155], v[192:195], v[54:57]
	v_mfma_f32_16x16x32_bf16 v[54:57], v[156:159], v[196:199], v[54:57]
	v_mfma_f32_16x16x32_bf16 v[38:41], v[152:155], v[206:209], v[38:41]
	v_mfma_f32_16x16x32_bf16 v[38:41], v[156:159], v[212:215], v[38:41]
	v_mfma_f32_16x16x32_bf16 v[22:25], v[152:155], v[220:223], v[22:25]
	v_mfma_f32_16x16x32_bf16 v[22:25], v[156:159], v[224:227], v[22:25]
	v_mfma_f32_16x16x32_bf16 v[58:61], v[160:163], v[184:187], v[58:61]
	v_mfma_f32_16x16x32_bf16 v[58:61], v[164:167], v[188:191], v[58:61]
	v_mfma_f32_16x16x32_bf16 v[46:49], v[160:163], v[192:195], v[46:49]
	v_mfma_f32_16x16x32_bf16 v[46:49], v[164:167], v[196:199], v[46:49]
	v_mfma_f32_16x16x32_bf16 v[30:33], v[160:163], v[206:209], v[30:33]
	v_mfma_f32_16x16x32_bf16 v[30:33], v[164:167], v[212:215], v[30:33]
	v_mfma_f32_16x16x32_bf16 v[14:17], v[160:163], v[220:223], v[14:17]
	v_mfma_f32_16x16x32_bf16 v[14:17], v[164:167], v[224:227], v[14:17]
	s_setprio 0
	s_setprio 1
	v_mfma_f32_16x16x32_bf16 v[50:53], v[168:171], v[184:187], v[50:53]
	v_mfma_f32_16x16x32_bf16 v[50:53], v[172:175], v[188:191], v[50:53]
	v_mfma_f32_16x16x32_bf16 v[34:37], v[168:171], v[192:195], v[34:37]
	v_mfma_f32_16x16x32_bf16 v[34:37], v[172:175], v[196:199], v[34:37]
	v_mfma_f32_16x16x32_bf16 v[18:21], v[168:171], v[206:209], v[18:21]
	v_mfma_f32_16x16x32_bf16 v[18:21], v[172:175], v[212:215], v[18:21]
	v_mfma_f32_16x16x32_bf16 v[6:9], v[168:171], v[220:223], v[6:9]
	v_mfma_f32_16x16x32_bf16 v[6:9], v[172:175], v[224:227], v[6:9]
	v_mfma_f32_16x16x32_bf16 v[42:45], v[176:179], v[184:187], v[42:45]
	v_mfma_f32_16x16x32_bf16 v[42:45], v[180:183], v[188:191], v[42:45]
	v_mfma_f32_16x16x32_bf16 v[26:29], v[176:179], v[192:195], v[26:29]
	v_mfma_f32_16x16x32_bf16 v[26:29], v[180:183], v[196:199], v[26:29]
	v_mfma_f32_16x16x32_bf16 v[10:13], v[176:179], v[206:209], v[10:13]
	v_mfma_f32_16x16x32_bf16 v[10:13], v[180:183], v[212:215], v[10:13]
	v_mfma_f32_16x16x32_bf16 v[2:5], v[176:179], v[220:223], v[2:5]
	v_mfma_f32_16x16x32_bf16 v[2:5], v[180:183], v[224:227], v[2:5]
	s_barrier
	s_setprio 0
	ds_read_b128 v[152:155], v150
	ds_read_b128 v[156:159], v150 offset:1024
	ds_read_b128 v[160:163], v150 offset:2048
	ds_read_b128 v[164:167], v150 offset:3072
	ds_read_b128 v[168:171], v151
	ds_read_b128 v[172:175], v151 offset:1024
	ds_read_b128 v[176:179], v151 offset:2048
	ds_read_b128 v[180:183], v151 offset:3072
	s_add_u32 s22, s22, 0x4000
	s_addc_u32 s23, s23, 0
	s_mov_b32 m0, s25
	ds_read_b128 v[184:187], v149 offset:32768
	ds_read_b128 v[188:191], v149 offset:33792
	ds_read_b128 v[192:195], v149 offset:34816
	ds_read_b128 v[196:199], v149 offset:35840
	ds_read_b128 v[206:209], v149 offset:36864
	ds_read_b128 v[212:215], v149 offset:37888
	ds_read_b128 v[220:223], v149 offset:38912
	ds_read_b128 v[224:227], v149 offset:39936
	global_load_lds_dwordx4 v136, s[22:23]
	s_mov_b32 m0, s26
	s_nop 0
	global_load_lds_dwordx4 v132, s[22:23]
	s_waitcnt vmcnt(8)
	s_waitcnt lgkmcnt(0)
	s_setprio 1
	s_barrier
	v_mfma_f32_16x16x32_bf16 v[126:129], v[152:155], v[184:187], v[126:129]
	v_mfma_f32_16x16x32_bf16 v[126:129], v[156:159], v[188:191], v[126:129]
	v_mfma_f32_16x16x32_bf16 v[118:121], v[152:155], v[192:195], v[118:121]
	v_mfma_f32_16x16x32_bf16 v[118:121], v[156:159], v[196:199], v[118:121]
	v_mfma_f32_16x16x32_bf16 v[102:105], v[152:155], v[206:209], v[102:105]
	v_mfma_f32_16x16x32_bf16 v[102:105], v[156:159], v[212:215], v[102:105]
	v_mfma_f32_16x16x32_bf16 v[86:89], v[152:155], v[220:223], v[86:89]
	v_mfma_f32_16x16x32_bf16 v[86:89], v[156:159], v[224:227], v[86:89]
	v_mfma_f32_16x16x32_bf16 v[122:125], v[160:163], v[184:187], v[122:125]
	v_mfma_f32_16x16x32_bf16 v[122:125], v[164:167], v[188:191], v[122:125]
	v_mfma_f32_16x16x32_bf16 v[110:113], v[160:163], v[192:195], v[110:113]
	v_mfma_f32_16x16x32_bf16 v[110:113], v[164:167], v[196:199], v[110:113]
	v_mfma_f32_16x16x32_bf16 v[94:97], v[160:163], v[206:209], v[94:97]
	v_mfma_f32_16x16x32_bf16 v[94:97], v[164:167], v[212:215], v[94:97]
	v_mfma_f32_16x16x32_bf16 v[78:81], v[160:163], v[220:223], v[78:81]
	v_mfma_f32_16x16x32_bf16 v[78:81], v[164:167], v[224:227], v[78:81]
	s_setprio 0
	s_setprio 1
	v_mfma_f32_16x16x32_bf16 v[114:117], v[168:171], v[184:187], v[114:117]
	v_mfma_f32_16x16x32_bf16 v[114:117], v[172:175], v[188:191], v[114:117]
	v_mfma_f32_16x16x32_bf16 v[98:101], v[168:171], v[192:195], v[98:101]
	v_mfma_f32_16x16x32_bf16 v[98:101], v[172:175], v[196:199], v[98:101]
	v_mfma_f32_16x16x32_bf16 v[82:85], v[168:171], v[206:209], v[82:85]
	v_mfma_f32_16x16x32_bf16 v[82:85], v[172:175], v[212:215], v[82:85]
	v_mfma_f32_16x16x32_bf16 v[70:73], v[168:171], v[220:223], v[70:73]
	v_mfma_f32_16x16x32_bf16 v[70:73], v[172:175], v[224:227], v[70:73]
	v_mfma_f32_16x16x32_bf16 v[106:109], v[176:179], v[184:187], v[106:109]
	v_mfma_f32_16x16x32_bf16 v[106:109], v[180:183], v[188:191], v[106:109]
	v_mfma_f32_16x16x32_bf16 v[90:93], v[176:179], v[192:195], v[90:93]
	v_mfma_f32_16x16x32_bf16 v[90:93], v[180:183], v[196:199], v[90:93]
	v_mfma_f32_16x16x32_bf16 v[74:77], v[176:179], v[206:209], v[74:77]
	v_mfma_f32_16x16x32_bf16 v[74:77], v[180:183], v[212:215], v[74:77]
	v_mfma_f32_16x16x32_bf16 v[66:69], v[176:179], v[220:223], v[66:69]
	v_mfma_f32_16x16x32_bf16 v[66:69], v[180:183], v[224:227], v[66:69]
	s_barrier
	s_setprio 0
	s_add_u32 s22, s20, 0x20000
	s_addc_u32 s23, s21, 0
	s_mov_b32 m0, s40
	s_add_u32 s20, s20, 0x24000
	ds_read_b128 v[184:187], v149 offset:49152
	ds_read_b128 v[188:191], v149 offset:50176
	ds_read_b128 v[192:195], v149 offset:51200
	ds_read_b128 v[196:199], v149 offset:52224
	ds_read_b128 v[206:209], v149 offset:53248
	ds_read_b128 v[212:215], v149 offset:54272
	ds_read_b128 v[220:223], v149 offset:55296
	ds_read_b128 v[224:227], v149 offset:56320
	global_load_lds_dwordx4 v134, s[22:23]
	s_mov_b32 m0, s41
	s_addc_u32 s21, s21, 0
	global_load_lds_dwordx4 v130, s[22:23]
	s_mov_b32 m0, s42
	s_nop 0
	global_load_lds_dwordx4 v134, s[20:21]
	s_mov_b32 m0, s43
	s_nop 0
	global_load_lds_dwordx4 v130, s[20:21]
	s_mov_b32 m0, s29
	s_nop 0
	global_load_lds_dwordx4 v136, s[18:19]
	s_mov_b32 m0, s30
	s_nop 0
	global_load_lds_dwordx4 v132, s[18:19]
	s_waitcnt vmcnt(8)
	s_waitcnt lgkmcnt(0)
	s_setprio 1
	s_barrier
	v_mfma_f32_16x16x32_bf16 v[62:65], v[152:155], v[184:187], v[62:65]
	v_mfma_f32_16x16x32_bf16 v[62:65], v[156:159], v[188:191], v[62:65]
	v_mfma_f32_16x16x32_bf16 v[54:57], v[152:155], v[192:195], v[54:57]
	v_mfma_f32_16x16x32_bf16 v[54:57], v[156:159], v[196:199], v[54:57]
	v_mfma_f32_16x16x32_bf16 v[38:41], v[152:155], v[206:209], v[38:41]
	v_mfma_f32_16x16x32_bf16 v[38:41], v[156:159], v[212:215], v[38:41]
	v_mfma_f32_16x16x32_bf16 v[22:25], v[152:155], v[220:223], v[22:25]
	v_mfma_f32_16x16x32_bf16 v[22:25], v[156:159], v[224:227], v[22:25]
	v_mfma_f32_16x16x32_bf16 v[58:61], v[160:163], v[184:187], v[58:61]
	v_mfma_f32_16x16x32_bf16 v[58:61], v[164:167], v[188:191], v[58:61]
	v_mfma_f32_16x16x32_bf16 v[46:49], v[160:163], v[192:195], v[46:49]
	v_mfma_f32_16x16x32_bf16 v[46:49], v[164:167], v[196:199], v[46:49]
	v_mfma_f32_16x16x32_bf16 v[30:33], v[160:163], v[206:209], v[30:33]
	v_mfma_f32_16x16x32_bf16 v[30:33], v[164:167], v[212:215], v[30:33]
	v_mfma_f32_16x16x32_bf16 v[14:17], v[160:163], v[220:223], v[14:17]
	v_mfma_f32_16x16x32_bf16 v[14:17], v[164:167], v[224:227], v[14:17]
	s_setprio 0
	s_setprio 1
	v_mfma_f32_16x16x32_bf16 v[50:53], v[168:171], v[184:187], v[50:53]
	v_mfma_f32_16x16x32_bf16 v[50:53], v[172:175], v[188:191], v[50:53]
	v_mfma_f32_16x16x32_bf16 v[34:37], v[168:171], v[192:195], v[34:37]
	v_mfma_f32_16x16x32_bf16 v[34:37], v[172:175], v[196:199], v[34:37]
	v_mfma_f32_16x16x32_bf16 v[18:21], v[168:171], v[206:209], v[18:21]
	v_mfma_f32_16x16x32_bf16 v[18:21], v[172:175], v[212:215], v[18:21]
	v_mfma_f32_16x16x32_bf16 v[6:9], v[168:171], v[220:223], v[6:9]
	v_mfma_f32_16x16x32_bf16 v[6:9], v[172:175], v[224:227], v[6:9]
	v_mfma_f32_16x16x32_bf16 v[42:45], v[176:179], v[184:187], v[42:45]
	v_mfma_f32_16x16x32_bf16 v[42:45], v[180:183], v[188:191], v[42:45]
	v_mfma_f32_16x16x32_bf16 v[26:29], v[176:179], v[192:195], v[26:29]
	v_mfma_f32_16x16x32_bf16 v[26:29], v[180:183], v[196:199], v[26:29]
	v_mfma_f32_16x16x32_bf16 v[10:13], v[176:179], v[206:209], v[10:13]
	v_mfma_f32_16x16x32_bf16 v[10:13], v[180:183], v[212:215], v[10:13]
	v_mfma_f32_16x16x32_bf16 v[2:5], v[176:179], v[220:223], v[2:5]
	v_mfma_f32_16x16x32_bf16 v[2:5], v[180:183], v[224:227], v[2:5]
	s_barrier
	s_setprio 0
	s_add_i32 s50, s50, 2
	s_add_u32 s48, s48, 0x40000
	s_addc_u32 s49, s49, 0
	s_add_u32 s16, s16, 0x10000
	s_addc_u32 s17, s17, 0
	s_cmp_gt_u32 s50, 61
	s_cbranch_scc0 .LBB0_1718
	v_mov_b32_e32 v138, v146
	s_lshl_b32 s16, s45, 8
	v_and_or_b32 v152, v138, 15, s27
	v_lshrrev_b32_e32 v138, 1, v138
	v_and_or_b32 v138, v138, 24, s16
	v_ashrrev_i32_e32 v153, 31, v152
	v_or_b32_e32 v138, s28, v138
	v_lshlrev_b64 v[144:145], 11, v[152:153]
	v_lshl_add_u64 v[144:145], s[8:9], 0, v[144:145]
	v_lshlrev_b64 v[154:155], 1, v[138:139]
	v_lshl_add_u64 v[144:145], v[144:145], 0, v[154:155]
	v_cvt_pk_bf16_f32 v126, v126, v127
	v_cvt_pk_bf16_f32 v127, v128, v129
	v_cvt_pk_bf16_f32 v128, v122, v123
	v_cvt_pk_bf16_f32 v129, v124, v125
	global_store_dwordx4 v[144:145], v[126:129], off
	v_cvt_pk_bf16_f32 v114, v114, v115
	v_cvt_pk_bf16_f32 v115, v116, v117
	v_cvt_pk_bf16_f32 v116, v106, v107
	v_or_b32_e32 v106, 16, v152
	v_ashrrev_i32_e32 v107, 31, v106
	v_lshlrev_b64 v[106:107], 11, v[106:107]
	v_lshl_add_u64 v[106:107], s[8:9], 0, v[106:107]
	v_cvt_pk_bf16_f32 v117, v108, v109
	global_store_dwordx4 v[144:145], v[114:117], off offset:256
	s_mov_b64 s[16:17], 0x40000
	s_cmp_eq_u32 s44, 4
	v_lshl_add_u64 v[114:115], v[106:107], 0, v[154:155]
	v_cvt_pk_bf16_f32 v106, v118, v119
	v_cvt_pk_bf16_f32 v107, v120, v121
	v_cvt_pk_bf16_f32 v108, v110, v111
	v_cvt_pk_bf16_f32 v109, v112, v113
	global_store_dwordx4 v[114:115], v[106:109], off
	v_cvt_pk_bf16_f32 v98, v98, v99
	v_cvt_pk_bf16_f32 v99, v100, v101
	v_cvt_pk_bf16_f32 v100, v90, v91
	v_or_b32_e32 v90, 32, v152
	v_ashrrev_i32_e32 v91, 31, v90
	v_lshlrev_b64 v[90:91], 11, v[90:91]
	v_lshl_add_u64 v[90:91], s[8:9], 0, v[90:91]
	v_cvt_pk_bf16_f32 v101, v92, v93
	global_store_dwordx4 v[114:115], v[98:101], off offset:256
	s_mov_b32 s45, s44
	s_nop 0
	v_lshl_add_u64 v[98:99], v[90:91], 0, v[154:155]
	v_cvt_pk_bf16_f32 v90, v102, v103
	v_cvt_pk_bf16_f32 v91, v104, v105
	v_cvt_pk_bf16_f32 v92, v94, v95
	v_cvt_pk_bf16_f32 v93, v96, v97
	global_store_dwordx4 v[98:99], v[90:93], off
	v_cvt_pk_bf16_f32 v82, v82, v83
	v_cvt_pk_bf16_f32 v83, v84, v85
	v_cvt_pk_bf16_f32 v84, v74, v75
	v_or_b32_e32 v74, 48, v152
	v_ashrrev_i32_e32 v75, 31, v74
	v_lshlrev_b64 v[74:75], 11, v[74:75]
	v_lshl_add_u64 v[74:75], s[8:9], 0, v[74:75]
	v_cvt_pk_bf16_f32 v85, v76, v77
	global_store_dwordx4 v[98:99], v[82:85], off offset:256
	s_nop 1
	v_lshl_add_u64 v[82:83], v[74:75], 0, v[154:155]
	v_cvt_pk_bf16_f32 v74, v86, v87
	v_cvt_pk_bf16_f32 v75, v88, v89
	v_cvt_pk_bf16_f32 v76, v78, v79
	v_cvt_pk_bf16_f32 v77, v80, v81
	global_store_dwordx4 v[82:83], v[74:77], off
	v_cvt_pk_bf16_f32 v70, v70, v71
	v_cvt_pk_bf16_f32 v71, v72, v73
	v_cvt_pk_bf16_f32 v72, v66, v67
	v_lshl_add_u64 v[66:67], v[144:145], 0, s[16:17]
	s_mov_b32 s16, 0x40000
	v_cvt_pk_bf16_f32 v73, v68, v69
	global_store_dwordx4 v[82:83], v[70:73], off offset:256
	v_cvt_pk_bf16_f32 v62, v62, v63
	v_cvt_pk_bf16_f32 v63, v64, v65
	v_cvt_pk_bf16_f32 v64, v58, v59
	v_add_co_u32_e32 v58, vcc, s16, v144
	v_cvt_pk_bf16_f32 v65, v60, v61
	s_mov_b64 s[16:17], 0x48000
	s_nop 0
	v_addc_co_u32_e32 v59, vcc, 0, v145, vcc
	global_store_dwordx4 v[58:59], v[62:65], off
	v_cvt_pk_bf16_f32 v50, v50, v51
	v_cvt_pk_bf16_f32 v51, v52, v53
	v_cvt_pk_bf16_f32 v52, v42, v43
	v_cvt_pk_bf16_f32 v53, v44, v45
	global_store_dwordx4 v[66:67], v[50:53], off offset:256
	v_cvt_pk_bf16_f32 v42, v54, v55
	v_cvt_pk_bf16_f32 v43, v56, v57
	v_cvt_pk_bf16_f32 v44, v46, v47
	v_cvt_pk_bf16_f32 v45, v48, v49
	s_nop 1
	v_lshl_add_u64 v[50:51], v[144:145], 0, s[16:17]
	s_mov_b32 s16, 0x48000
	v_add_co_u32_e32 v46, vcc, s16, v144
	s_mov_b64 s[16:17], s[10:11]
	s_nop 0
	v_addc_co_u32_e32 v47, vcc, 0, v145, vcc
	global_store_dwordx4 v[46:47], v[42:45], off
	v_cvt_pk_bf16_f32 v34, v34, v35
	v_cvt_pk_bf16_f32 v35, v36, v37
	v_cvt_pk_bf16_f32 v36, v26, v27
	v_cvt_pk_bf16_f32 v37, v28, v29
	global_store_dwordx4 v[50:51], v[34:37], off offset:256
	v_cvt_pk_bf16_f32 v26, v38, v39
	v_cvt_pk_bf16_f32 v27, v40, v41
	v_cvt_pk_bf16_f32 v28, v30, v31
	v_add_co_u32_e32 v30, vcc, s34, v144
	s_nop 0
	v_lshl_add_u64 v[34:35], v[144:145], 0, s[4:5]
	v_addc_co_u32_e32 v31, vcc, 0, v145, vcc
	v_cvt_pk_bf16_f32 v29, v32, v33
	global_store_dwordx4 v[30:31], v[26:29], off
	v_cvt_pk_bf16_f32 v18, v18, v19
	v_cvt_pk_bf16_f32 v19, v20, v21
	v_cvt_pk_bf16_f32 v20, v10, v11
	v_cvt_pk_bf16_f32 v21, v12, v13
	global_store_dwordx4 v[34:35], v[18:21], off offset:256
	v_cvt_pk_bf16_f32 v10, v22, v23
	v_cvt_pk_bf16_f32 v11, v24, v25
	v_cvt_pk_bf16_f32 v12, v14, v15
	v_add_co_u32_e32 v14, vcc, s35, v144
	s_nop 0
	v_lshl_add_u64 v[18:19], v[144:145], 0, s[6:7]
	v_addc_co_u32_e32 v15, vcc, 0, v145, vcc
	v_cvt_pk_bf16_f32 v13, v16, v17
	global_store_dwordx4 v[14:15], v[10:13], off
	v_cvt_pk_bf16_f32 v6, v6, v7
	v_cvt_pk_bf16_f32 v7, v8, v9
	v_cvt_pk_bf16_f32 v8, v2, v3
	v_cvt_pk_bf16_f32 v9, v4, v5
	global_store_dwordx4 v[18:19], v[6:9], off offset:256
	s_cbranch_scc0 .LBB0_1717
	s_waitcnt vmcnt(0)
	s_cmpk_gt_u32 s0, 0xff
	s_cbranch_scc1 .LBB0_1722
	s_barrier

.LBB0_2185:
	ds_read_b128 v[146:149], v152
	ds_read_b128 v[156:159], v152 offset:1024
	ds_read_b128 v[160:163], v152 offset:2048
	ds_read_b128 v[164:167], v152 offset:3072
	ds_read_b128 v[168:171], v153
	ds_read_b128 v[172:175], v153 offset:1024
	ds_read_b128 v[176:179], v153 offset:2048
	ds_read_b128 v[180:183], v153 offset:3072
	s_add_u32 s22, s20, 0xfc000
	s_addc_u32 s23, s21, 0
	s_cmp_eq_u32 s44, 4
	s_cselect_b32 s26, s15, s22
	s_cselect_b32 s27, s5, s23
	s_cselect_b32 s24, s41, s42
	s_cselect_b32 s25, s13, s43
	s_add_u32 s22, s26, 0x100000
	s_addc_u32 s23, s27, 0
	s_add_i32 m0, s1, 0xc000
	ds_read_b128 v[184:187], v154
	ds_read_b128 v[188:191], v154 offset:1024
	ds_read_b128 v[192:195], v154 offset:2048
	ds_read_b128 v[196:199], v154 offset:3072
	ds_read_b128 v[206:209], v154 offset:4096
	ds_read_b128 v[212:215], v154 offset:5120
	ds_read_b128 v[220:223], v154 offset:6144
	ds_read_b128 v[224:227], v154 offset:7168
	global_load_lds_dwordx4 v138, s[20:21]
	s_add_i32 m0, s1, 0xe000
	s_nop 0
	global_load_lds_dwordx4 v140, s[20:21]
	s_waitcnt vmcnt(8)
	s_waitcnt lgkmcnt(0)
	s_setprio 1
	s_barrier
	v_mfma_f32_16x16x32_bf16 v[126:129], v[146:149], v[184:187], v[126:129]
	v_mfma_f32_16x16x32_bf16 v[126:129], v[156:159], v[188:191], v[126:129]
	v_mfma_f32_16x16x32_bf16 v[110:113], v[146:149], v[192:195], v[110:113]
	v_mfma_f32_16x16x32_bf16 v[110:113], v[156:159], v[196:199], v[110:113]
	v_mfma_f32_16x16x32_bf16 v[94:97], v[146:149], v[206:209], v[94:97]
	v_mfma_f32_16x16x32_bf16 v[94:97], v[156:159], v[212:215], v[94:97]
	v_mfma_f32_16x16x32_bf16 v[78:81], v[146:149], v[220:223], v[78:81]
	v_mfma_f32_16x16x32_bf16 v[78:81], v[156:159], v[224:227], v[78:81]
	v_mfma_f32_16x16x32_bf16 v[122:125], v[160:163], v[184:187], v[122:125]
	v_mfma_f32_16x16x32_bf16 v[122:125], v[164:167], v[188:191], v[122:125]
	v_mfma_f32_16x16x32_bf16 v[106:109], v[160:163], v[192:195], v[106:109]
	v_mfma_f32_16x16x32_bf16 v[106:109], v[164:167], v[196:199], v[106:109]
	v_mfma_f32_16x16x32_bf16 v[90:93], v[160:163], v[206:209], v[90:93]
	v_mfma_f32_16x16x32_bf16 v[90:93], v[164:167], v[212:215], v[90:93]
	v_mfma_f32_16x16x32_bf16 v[74:77], v[160:163], v[220:223], v[74:77]
	v_mfma_f32_16x16x32_bf16 v[74:77], v[164:167], v[224:227], v[74:77]
	s_setprio 0
	s_setprio 1
	v_mfma_f32_16x16x32_bf16 v[118:121], v[168:171], v[184:187], v[118:121]
	v_mfma_f32_16x16x32_bf16 v[118:121], v[172:175], v[188:191], v[118:121]
	v_mfma_f32_16x16x32_bf16 v[102:105], v[168:171], v[192:195], v[102:105]
	v_mfma_f32_16x16x32_bf16 v[102:105], v[172:175], v[196:199], v[102:105]
	v_mfma_f32_16x16x32_bf16 v[86:89], v[168:171], v[206:209], v[86:89]
	v_mfma_f32_16x16x32_bf16 v[86:89], v[172:175], v[212:215], v[86:89]
	v_mfma_f32_16x16x32_bf16 v[70:73], v[168:171], v[220:223], v[70:73]
	v_mfma_f32_16x16x32_bf16 v[70:73], v[172:175], v[224:227], v[70:73]
	v_mfma_f32_16x16x32_bf16 v[114:117], v[176:179], v[184:187], v[114:117]
	v_mfma_f32_16x16x32_bf16 v[114:117], v[180:183], v[188:191], v[114:117]
	v_mfma_f32_16x16x32_bf16 v[98:101], v[176:179], v[192:195], v[98:101]
	v_mfma_f32_16x16x32_bf16 v[98:101], v[180:183], v[196:199], v[98:101]
	v_mfma_f32_16x16x32_bf16 v[82:85], v[176:179], v[206:209], v[82:85]
	v_mfma_f32_16x16x32_bf16 v[82:85], v[180:183], v[212:215], v[82:85]
	v_mfma_f32_16x16x32_bf16 v[66:69], v[176:179], v[220:223], v[66:69]
	v_mfma_f32_16x16x32_bf16 v[66:69], v[180:183], v[224:227], v[66:69]
	s_barrier
	s_setprio 0
	s_add_i32 s45, s38, s0
	s_mov_b32 m0, s45
	ds_read_b128 v[184:187], v154 offset:16384
	ds_read_b128 v[188:191], v154 offset:17408
	ds_read_b128 v[192:195], v154 offset:18432
	ds_read_b128 v[196:199], v154 offset:19456
	ds_read_b128 v[206:209], v154 offset:20480
	ds_read_b128 v[212:215], v154 offset:21504
	ds_read_b128 v[220:223], v154 offset:22528
	ds_read_b128 v[224:227], v154 offset:23552
	global_load_lds_dwordx4 v132, s[24:25]
	s_add_i32 m0, s45, 0x2000
	s_add_u32 s46, s24, 0x4000
	s_addc_u32 s47, s25, 0
	s_add_i32 s45, s39, s0
	global_load_lds_dwordx4 v136, s[24:25]
	s_mov_b32 m0, s45
	s_nop 0
	global_load_lds_dwordx4 v132, s[46:47]
	s_add_i32 m0, s45, 0x2000
	s_nop 0
	global_load_lds_dwordx4 v136, s[46:47]
	s_mov_b32 m0, s1
	s_nop 0
	global_load_lds_dwordx4 v130, s[26:27]
	s_mov_b32 m0, s28
	s_nop 0
	global_load_lds_dwordx4 v134, s[26:27]
	s_waitcnt vmcnt(8)
	s_waitcnt lgkmcnt(0)
	s_setprio 1
	s_barrier
	v_mfma_f32_16x16x32_bf16 v[62:65], v[146:149], v[184:187], v[62:65]
	v_mfma_f32_16x16x32_bf16 v[62:65], v[156:159], v[188:191], v[62:65]
	v_mfma_f32_16x16x32_bf16 v[46:49], v[146:149], v[192:195], v[46:49]
	v_mfma_f32_16x16x32_bf16 v[46:49], v[156:159], v[196:199], v[46:49]
	v_mfma_f32_16x16x32_bf16 v[30:33], v[146:149], v[206:209], v[30:33]
	v_mfma_f32_16x16x32_bf16 v[30:33], v[156:159], v[212:215], v[30:33]
	v_mfma_f32_16x16x32_bf16 v[14:17], v[146:149], v[220:223], v[14:17]
	v_mfma_f32_16x16x32_bf16 v[14:17], v[156:159], v[224:227], v[14:17]
	v_mfma_f32_16x16x32_bf16 v[58:61], v[160:163], v[184:187], v[58:61]
	v_mfma_f32_16x16x32_bf16 v[58:61], v[164:167], v[188:191], v[58:61]
	v_mfma_f32_16x16x32_bf16 v[42:45], v[160:163], v[192:195], v[42:45]
	v_mfma_f32_16x16x32_bf16 v[42:45], v[164:167], v[196:199], v[42:45]
	v_mfma_f32_16x16x32_bf16 v[26:29], v[160:163], v[206:209], v[26:29]
	v_mfma_f32_16x16x32_bf16 v[26:29], v[164:167], v[212:215], v[26:29]
	v_mfma_f32_16x16x32_bf16 v[10:13], v[160:163], v[220:223], v[10:13]
	v_mfma_f32_16x16x32_bf16 v[10:13], v[164:167], v[224:227], v[10:13]
	s_setprio 0
	s_setprio 1
	v_mfma_f32_16x16x32_bf16 v[54:57], v[168:171], v[184:187], v[54:57]
	v_mfma_f32_16x16x32_bf16 v[54:57], v[172:175], v[188:191], v[54:57]
	v_mfma_f32_16x16x32_bf16 v[38:41], v[168:171], v[192:195], v[38:41]
	v_mfma_f32_16x16x32_bf16 v[38:41], v[172:175], v[196:199], v[38:41]
	v_mfma_f32_16x16x32_bf16 v[22:25], v[168:171], v[206:209], v[22:25]
	v_mfma_f32_16x16x32_bf16 v[22:25], v[172:175], v[212:215], v[22:25]
	v_mfma_f32_16x16x32_bf16 v[6:9], v[168:171], v[220:223], v[6:9]
	v_mfma_f32_16x16x32_bf16 v[6:9], v[172:175], v[224:227], v[6:9]
	v_mfma_f32_16x16x32_bf16 v[50:53], v[176:179], v[184:187], v[50:53]
	v_mfma_f32_16x16x32_bf16 v[50:53], v[180:183], v[188:191], v[50:53]
	v_mfma_f32_16x16x32_bf16 v[34:37], v[176:179], v[192:195], v[34:37]
	v_mfma_f32_16x16x32_bf16 v[34:37], v[180:183], v[196:199], v[34:37]
	v_mfma_f32_16x16x32_bf16 v[18:21], v[176:179], v[206:209], v[18:21]
	v_mfma_f32_16x16x32_bf16 v[18:21], v[180:183], v[212:215], v[18:21]
	v_mfma_f32_16x16x32_bf16 v[2:5], v[176:179], v[220:223], v[2:5]
	v_mfma_f32_16x16x32_bf16 v[2:5], v[180:183], v[224:227], v[2:5]
	s_barrier
	s_setprio 0
	s_add_i32 s45, 0, 0x18000
	v_add_u32_e32 v155, s45, v151
	s_add_i32 s46, 0, 0x1c000
	ds_read_b128 v[146:149], v155
	ds_read_b128 v[156:159], v155 offset:1024
	ds_read_b128 v[160:163], v155 offset:2048
	ds_read_b128 v[164:167], v155 offset:3072
	v_add_u32_e32 v155, s46, v151
	ds_read_b128 v[168:171], v155
	ds_read_b128 v[172:175], v155 offset:1024
	ds_read_b128 v[176:179], v155 offset:2048
	ds_read_b128 v[180:183], v155 offset:3072
	s_add_u32 s26, s26, 0x4000
	s_addc_u32 s27, s27, 0
	s_mov_b32 m0, s29
	ds_read_b128 v[184:187], v154 offset:32768
	ds_read_b128 v[188:191], v154 offset:33792
	ds_read_b128 v[192:195], v154 offset:34816
	ds_read_b128 v[196:199], v154 offset:35840
	ds_read_b128 v[206:209], v154 offset:36864
	ds_read_b128 v[212:215], v154 offset:37888
	ds_read_b128 v[220:223], v154 offset:38912
	ds_read_b128 v[224:227], v154 offset:39936
	global_load_lds_dwordx4 v130, s[26:27]
	s_mov_b32 m0, s30
	s_nop 0
	global_load_lds_dwordx4 v134, s[26:27]
	s_waitcnt vmcnt(8)
	s_waitcnt lgkmcnt(0)
	s_setprio 1
	s_barrier
	v_mfma_f32_16x16x32_bf16 v[126:129], v[146:149], v[184:187], v[126:129]
	v_mfma_f32_16x16x32_bf16 v[126:129], v[156:159], v[188:191], v[126:129]
	v_mfma_f32_16x16x32_bf16 v[110:113], v[146:149], v[192:195], v[110:113]
	v_mfma_f32_16x16x32_bf16 v[110:113], v[156:159], v[196:199], v[110:113]
	v_mfma_f32_16x16x32_bf16 v[94:97], v[146:149], v[206:209], v[94:97]
	v_mfma_f32_16x16x32_bf16 v[94:97], v[156:159], v[212:215], v[94:97]
	v_mfma_f32_16x16x32_bf16 v[78:81], v[146:149], v[220:223], v[78:81]
	v_mfma_f32_16x16x32_bf16 v[78:81], v[156:159], v[224:227], v[78:81]
	v_mfma_f32_16x16x32_bf16 v[122:125], v[160:163], v[184:187], v[122:125]
	v_mfma_f32_16x16x32_bf16 v[122:125], v[164:167], v[188:191], v[122:125]
	v_mfma_f32_16x16x32_bf16 v[106:109], v[160:163], v[192:195], v[106:109]
	v_mfma_f32_16x16x32_bf16 v[106:109], v[164:167], v[196:199], v[106:109]
	v_mfma_f32_16x16x32_bf16 v[90:93], v[160:163], v[206:209], v[90:93]
	v_mfma_f32_16x16x32_bf16 v[90:93], v[164:167], v[212:215], v[90:93]
	v_mfma_f32_16x16x32_bf16 v[74:77], v[160:163], v[220:223], v[74:77]
	v_mfma_f32_16x16x32_bf16 v[74:77], v[164:167], v[224:227], v[74:77]
	s_setprio 0
	s_setprio 1
	v_mfma_f32_16x16x32_bf16 v[118:121], v[168:171], v[184:187], v[118:121]
	v_mfma_f32_16x16x32_bf16 v[118:121], v[172:175], v[188:191], v[118:121]
	v_mfma_f32_16x16x32_bf16 v[102:105], v[168:171], v[192:195], v[102:105]
	v_mfma_f32_16x16x32_bf16 v[102:105], v[172:175], v[196:199], v[102:105]
	v_mfma_f32_16x16x32_bf16 v[86:89], v[168:171], v[206:209], v[86:89]
	v_mfma_f32_16x16x32_bf16 v[86:89], v[172:175], v[212:215], v[86:89]
	v_mfma_f32_16x16x32_bf16 v[70:73], v[168:171], v[220:223], v[70:73]
	v_mfma_f32_16x16x32_bf16 v[70:73], v[172:175], v[224:227], v[70:73]
	v_mfma_f32_16x16x32_bf16 v[114:117], v[176:179], v[184:187], v[114:117]
	v_mfma_f32_16x16x32_bf16 v[114:117], v[180:183], v[188:191], v[114:117]
	v_mfma_f32_16x16x32_bf16 v[98:101], v[176:179], v[192:195], v[98:101]
	v_mfma_f32_16x16x32_bf16 v[98:101], v[180:183], v[196:199], v[98:101]
	v_mfma_f32_16x16x32_bf16 v[82:85], v[176:179], v[206:209], v[82:85]
	v_mfma_f32_16x16x32_bf16 v[82:85], v[180:183], v[212:215], v[82:85]
	v_mfma_f32_16x16x32_bf16 v[66:69], v[176:179], v[220:223], v[66:69]
	v_mfma_f32_16x16x32_bf16 v[66:69], v[180:183], v[224:227], v[66:69]
	s_barrier
	s_setprio 0
	s_add_u32 s26, s24, 0x80000
	s_addc_u32 s27, s25, 0
	s_add_i32 s45, s45, s0
	s_mov_b32 m0, s45
	ds_read_b128 v[184:187], v154 offset:49152
	ds_read_b128 v[188:191], v154 offset:50176
	ds_read_b128 v[192:195], v154 offset:51200
	ds_read_b128 v[196:199], v154 offset:52224
	ds_read_b128 v[206:209], v154 offset:53248
	ds_read_b128 v[212:215], v154 offset:54272
	ds_read_b128 v[220:223], v154 offset:55296
	ds_read_b128 v[224:227], v154 offset:56320
	global_load_lds_dwordx4 v132, s[26:27]
	s_add_i32 m0, s45, 0x2000
	s_add_u32 s24, s24, 0x84000
	s_addc_u32 s25, s25, 0
	global_load_lds_dwordx4 v136, s[26:27]
	s_add_i32 s26, s46, s0
	s_mov_b32 m0, s26
	s_nop 0
	global_load_lds_dwordx4 v132, s[24:25]
	s_add_i32 m0, s26, 0x2000
	s_nop 0
	global_load_lds_dwordx4 v136, s[24:25]
	s_mov_b32 m0, s36
	s_nop 0
	global_load_lds_dwordx4 v130, s[22:23]
	s_mov_b32 m0, s37
	s_nop 0
	global_load_lds_dwordx4 v134, s[22:23]
	s_waitcnt vmcnt(8)
	s_waitcnt lgkmcnt(0)
	s_setprio 1
	s_barrier
	v_mfma_f32_16x16x32_bf16 v[62:65], v[146:149], v[184:187], v[62:65]
	v_mfma_f32_16x16x32_bf16 v[62:65], v[156:159], v[188:191], v[62:65]
	v_mfma_f32_16x16x32_bf16 v[46:49], v[146:149], v[192:195], v[46:49]
	v_mfma_f32_16x16x32_bf16 v[46:49], v[156:159], v[196:199], v[46:49]
	v_mfma_f32_16x16x32_bf16 v[30:33], v[146:149], v[206:209], v[30:33]
	v_mfma_f32_16x16x32_bf16 v[30:33], v[156:159], v[212:215], v[30:33]
	v_mfma_f32_16x16x32_bf16 v[14:17], v[146:149], v[220:223], v[14:17]
	v_mfma_f32_16x16x32_bf16 v[14:17], v[156:159], v[224:227], v[14:17]
	v_mfma_f32_16x16x32_bf16 v[58:61], v[160:163], v[184:187], v[58:61]
	v_mfma_f32_16x16x32_bf16 v[58:61], v[164:167], v[188:191], v[58:61]
	v_mfma_f32_16x16x32_bf16 v[42:45], v[160:163], v[192:195], v[42:45]
	v_mfma_f32_16x16x32_bf16 v[42:45], v[164:167], v[196:199], v[42:45]
	v_mfma_f32_16x16x32_bf16 v[26:29], v[160:163], v[206:209], v[26:29]
	v_mfma_f32_16x16x32_bf16 v[26:29], v[164:167], v[212:215], v[26:29]
	v_mfma_f32_16x16x32_bf16 v[10:13], v[160:163], v[220:223], v[10:13]
	v_mfma_f32_16x16x32_bf16 v[10:13], v[164:167], v[224:227], v[10:13]
	s_setprio 0
	s_setprio 1
	v_mfma_f32_16x16x32_bf16 v[54:57], v[168:171], v[184:187], v[54:57]
	v_mfma_f32_16x16x32_bf16 v[54:57], v[172:175], v[188:191], v[54:57]
	v_mfma_f32_16x16x32_bf16 v[38:41], v[168:171], v[192:195], v[38:41]
	v_mfma_f32_16x16x32_bf16 v[38:41], v[172:175], v[196:199], v[38:41]
	v_mfma_f32_16x16x32_bf16 v[22:25], v[168:171], v[206:209], v[22:25]
	v_mfma_f32_16x16x32_bf16 v[22:25], v[172:175], v[212:215], v[22:25]
	v_mfma_f32_16x16x32_bf16 v[6:9], v[168:171], v[220:223], v[6:9]
	v_mfma_f32_16x16x32_bf16 v[6:9], v[172:175], v[224:227], v[6:9]
	v_mfma_f32_16x16x32_bf16 v[50:53], v[176:179], v[184:187], v[50:53]
	v_mfma_f32_16x16x32_bf16 v[50:53], v[180:183], v[188:191], v[50:53]
	v_mfma_f32_16x16x32_bf16 v[34:37], v[176:179], v[192:195], v[34:37]
	v_mfma_f32_16x16x32_bf16 v[34:37], v[180:183], v[196:199], v[34:37]
	v_mfma_f32_16x16x32_bf16 v[18:21], v[176:179], v[206:209], v[18:21]
	v_mfma_f32_16x16x32_bf16 v[18:21], v[180:183], v[212:215], v[18:21]
	v_mfma_f32_16x16x32_bf16 v[2:5], v[176:179], v[220:223], v[2:5]
	v_mfma_f32_16x16x32_bf16 v[2:5], v[180:183], v[224:227], v[2:5]
	s_barrier
	s_setprio 0
	s_add_i32 s44, s44, 2
	s_add_u32 s42, s42, 0x100000
	s_addc_u32 s43, s43, 0
	s_add_u32 s20, s20, 0x200000
	s_addc_u32 s21, s21, 0
	s_cmp_gt_u32 s44, 5
	s_cbranch_scc0 .LBB0_2185
	s_and_b64 vcc, exec, s[8:9]
	s_cbranch_vccz .LBB0_2188
	s_barrier
